# P13: bf16 input samples of each FFT pair prefetched one pair ahead into spare VGPRs (latency hidden behind previous pair / filter FFT)
# baseline (speedup 1.0000x reference)
; __device__ __forceinline__ float bfl(unsigned w) { return __uint_as_float(w << 16); }
; #define tid ltid()
; #define G lgrid()
; #define bx lbid()
; template <int LR>
; __device__ __forceinline__ void fft_first(float2* X, const bf16* __restrict__ u0, const bf16* __restrict__ u1, const int tid) {
;     ...
;   for (int m = 0; m < R / 2; ++m) x[m] = make_float2(bfl(u0[tid + 512 * m]), bfl(u1[tid + 512 * m]));
; __global__ void __launch_bounds__(NTHR, 2) mega_fwd(Args a_unused) {
;     ...
;         for (int u = bx; u < 4096; u += G) {
;           const int gsel = u < 2048 ? 1 : 0, c = u & 2047;
;           const int L = gsel ? 4096 : 2048, N = 2 * L;
;           const float* hd = (const float*)(ws + (gsel ? WS_HDN_S : WS_HDN_P));
;           __syncthreads();
;           { const float* frow = (const float*)((const char*)AOUT + 192 * MiB) + (gsel ? (size_t)c * 8192 : (size_t)2048 * 8192 + (size_t)c * 4096);
;             for (int n = tid; n < N; n += NTHR) Hb[PIDX(n)] = make_float2(frow[n], 0.f); }
;           __syncthreads();
.LBB0_645:
	s_cmpk_gt_i32 s5, 0x7ff
	s_cselect_b64 s[10:11], -1, 0
	s_and_b32 s17, s5, 0x7ff
	s_cmpk_lt_i32 s5, 0x800
	s_cselect_b64 s[42:43], -1, 0
	s_and_b64 s[12:13], s[42:43], exec
	s_movk_i32 s12, 0x800
	s_cselect_b32 s16, 0x1000, s12
	s_lshl_b32 s18, s16, 1
	s_mov_b64 s[12:13], s[0:1]
	s_mov_b64 s[14:15], s[0:1]
	v_mov_b32_e32 v0, v208
	s_waitcnt lgkmcnt(0)
	s_barrier
	s_mul_i32 s57, s17, 0x18000
	s_add_u32 s58, s8, s57
	s_addc_u32 s59, s9, 0
	s_and_b64 s[60:61], s[42:43], exec
	s_cselect_b32 s57, 0x8000, 0
	s_add_u32 s58, s58, s57
	s_addc_u32 s59, s59, 0
	s_lshl_b32 s62, s16, 1
	s_add_u32 s60, s58, s62
	s_addc_u32 s61, s59, 0
	v_lshlrev_b32_e32 v238, 1, v208
	v_mov_b32_e32 v239, 0
	v_lshl_add_u64 v[234:235], s[58:59], 0, v[238:239]
	v_lshl_add_u64 v[236:237], s[60:61], 0, v[238:239]
	global_load_ushort v218, v[234:235], off
	global_load_ushort v219, v[236:237], off
	global_load_ushort v220, v[234:235], off offset:1024
	global_load_ushort v221, v[236:237], off offset:1024
	global_load_ushort v222, v[234:235], off offset:2048
	global_load_ushort v223, v[236:237], off offset:2048
	global_load_ushort v224, v[234:235], off offset:3072
	global_load_ushort v225, v[236:237], off offset:3072
	s_cmp_lg_u32 s18, 0x2000
	s_cbranch_scc1 .Lpf_unit_half
	s_mov_b64 s[96:97], 0x1000
	v_lshl_add_u64 v[234:235], v[234:235], 0, s[96:97]
	v_lshl_add_u64 v[236:237], v[236:237], 0, s[96:97]
	global_load_ushort v226, v[234:235], off
	global_load_ushort v227, v[236:237], off
	global_load_ushort v228, v[234:235], off offset:1024
	global_load_ushort v229, v[236:237], off offset:1024
	global_load_ushort v230, v[234:235], off offset:2048
	global_load_ushort v231, v[236:237], off offset:2048
	global_load_ushort v232, v[234:235], off offset:3072
	global_load_ushort v233, v[236:237], off offset:3072
.Lpf_unit_half:
	s_nop 0
	v_cmp_gt_i32_e32 vcc, s18, v0
	s_and_saveexec_b64 s[12:13], vcc
	s_cbranch_execz .LBB0_648
	s_load_dwordx2 s[14:15], s[14:15], 0xe8
	s_lshl_b32 s20, s17, 12
	s_lshl_b32 s19, s17, 13
	s_or_b32 s22, s20, 0x1000000
	s_and_b64 s[20:21], s[42:43], exec
	s_cselect_b32 s19, s19, s22
	s_lshl_b32 s19, s19, 2
	s_waitcnt lgkmcnt(0)
	s_add_u32 s14, s14, s19
	v_ashrrev_i32_e32 v1, 31, v0
	s_addc_u32 s15, s15, 0
	v_lshl_add_u64 v[2:3], v[0:1], 2, s[14:15]
	s_mov_b64 s[14:15], 0xc000000
	v_lshl_add_u64 v[2:3], v[2:3], 0, s[14:15]
	v_lshl_add_u32 v1, v0, 3, s52
	v_ashrrev_i32_e32 v4, 4, v0
	v_lshl_add_u32 v4, v4, 3, v1
	s_mov_b64 s[20:21], 0x1000
	v_mov_b32_e32 v151, 0
	v_mov_b32_e32 v153, 0
	v_mov_b32_e32 v155, 0
	v_mov_b32_e32 v157, 0
	v_mov_b32_e32 v159, 0
	v_mov_b32_e32 v161, 0
	v_mov_b32_e32 v163, 0
	v_mov_b32_e32 v165, 0
	v_mov_b32_e32 v167, 0
	v_mov_b32_e32 v169, 0
	v_mov_b32_e32 v171, 0
	v_mov_b32_e32 v173, 0
	v_mov_b32_e32 v175, 0
	v_mov_b32_e32 v177, 0
	v_mov_b32_e32 v179, 0
	v_mov_b32_e32 v181, 0
	global_load_dword v150, v[2:3], off
	global_load_dword v152, v[2:3], off offset:2048
	v_lshl_add_u64 v[2:3], v[2:3], 0, s[20:21]
	global_load_dword v154, v[2:3], off
	global_load_dword v156, v[2:3], off offset:2048
	v_lshl_add_u64 v[2:3], v[2:3], 0, s[20:21]
	global_load_dword v158, v[2:3], off
	global_load_dword v160, v[2:3], off offset:2048
	v_lshl_add_u64 v[2:3], v[2:3], 0, s[20:21]
	global_load_dword v162, v[2:3], off
	global_load_dword v164, v[2:3], off offset:2048
	v_lshl_add_u64 v[2:3], v[2:3], 0, s[20:21]
	s_cmp_lg_u32 s18, 0x2000
	s_cbranch_scc1 .Lfload_half
	global_load_dword v166, v[2:3], off
	global_load_dword v168, v[2:3], off offset:2048
	v_lshl_add_u64 v[2:3], v[2:3], 0, s[20:21]
	global_load_dword v170, v[2:3], off
	global_load_dword v172, v[2:3], off offset:2048
	v_lshl_add_u64 v[2:3], v[2:3], 0, s[20:21]
	global_load_dword v174, v[2:3], off
	global_load_dword v176, v[2:3], off offset:2048
	v_lshl_add_u64 v[2:3], v[2:3], 0, s[20:21]
	global_load_dword v178, v[2:3], off
	global_load_dword v180, v[2:3], off offset:2048
	s_waitcnt vmcnt(8)
	ds_write_b64 v4, v[150:151] offset:0
	ds_write_b64 v4, v[152:153] offset:4352
	ds_write_b64 v4, v[154:155] offset:8704
	ds_write_b64 v4, v[156:157] offset:13056
	ds_write_b64 v4, v[158:159] offset:17408
	ds_write_b64 v4, v[160:161] offset:21760
	ds_write_b64 v4, v[162:163] offset:26112
	ds_write_b64 v4, v[164:165] offset:30464
	s_waitcnt vmcnt(0)
	ds_write_b64 v4, v[166:167] offset:34816
	ds_write_b64 v4, v[168:169] offset:39168
	ds_write_b64 v4, v[170:171] offset:43520
	ds_write_b64 v4, v[172:173] offset:47872
	ds_write_b64 v4, v[174:175] offset:52224
	ds_write_b64 v4, v[176:177] offset:56576
	ds_write_b64 v4, v[178:179] offset:60928
	ds_write_b64 v4, v[180:181] offset:65280
	s_branch .LBB0_648

; __global__ void __launch_bounds__(NTHR, 2) mega_fwd(Args a_unused) {
;     ...
;           const float invN = 1.0f / (float)N;
;           const size_t sbase = gsel ? (size_t)TP : 0;
;           bf16* urow = UT + (size_t)c * T_TOK + sbase;
; #pragma unroll 1
;           for (int pr = 0; pr < 4; ++pr) {
;             bf16* u0 = urow + (size_t)(2 * pr) * L; bf16* u1 = u0 + L;
.LBB0_667:
	s_or_b64 exec, exec, s[12:13]
	v_cvt_f32_u32_e32 v0, s18
	s_and_b64 s[12:13], s[42:43], exec
	s_mul_i32 s17, s17, 0x18000
	s_mov_b32 s18, 0
	v_div_scale_f32 v1, s[12:13], v0, v0, 1.0
	v_rcp_f32_e32 v2, v1
	v_div_scale_f32 v3, vcc, 1.0, v0, 1.0
	s_cselect_b32 s12, 0x8000, 0
	v_fma_f32 v4, -v1, v2, 1.0
	v_fmac_f32_e32 v2, v4, v2
	v_mul_f32_e32 v4, v3, v2
	v_fma_f32 v5, -v1, v4, v3
	s_add_u32 s13, s8, s17
	v_fmac_f32_e32 v4, v5, v2
	s_addc_u32 s14, s9, 0
	v_fma_f32 v1, -v1, v4, v3
	s_add_u32 s17, s13, s12
	v_div_fmas_f32 v1, v1, v2, v4
	s_addc_u32 s19, s14, 0
	v_div_fixup_f32 v0, v1, v0, 1.0
	s_and_b64 s[12:13], s[42:43], exec
	s_cselect_b32 s20, 12, 11
	s_lshr_b32 s21, s16, 2
	v_mov_b32_e32 v1, v0
	s_lshl_b32 s16, s16, 1
	s_waitcnt vmcnt(0)
	s_waitcnt lgkmcnt(0)
	s_barrier
	s_branch .LBB0_669

; __device__ __forceinline__ float bfl(unsigned w) { return __uint_as_float(w << 16); }
; __device__ __forceinline__ float2 cmul(float2 a, float2 b) { return make_float2(a.x * b.x - a.y * b.y, a.x * b.y + a.y * b.x); }
; #define tid ltid()
; template <int LR, bool INV>
; __device__ __forceinline__ void fft_stages(float2 (&x)[1 << LR], const int r, const int s) {
;     ...
;   for (int st = 0; st < LR; ++st) {
;     const int hl = INV ? (1 << st) : (R >> (st + 1));
;     const float fb = (float)r * (0.5f / (float)(hl * s));
;     const float2 wb = make_float2(__builtin_amdgcn_cosf(fb), INV ? __builtin_amdgcn_sinf(fb) : -__builtin_amdgcn_sinf(fb));
; #pragma unroll
;     for (int m = 0; m < R; ++m) {
;       if (m & hl) continue;
;       const int k = m & (hl - 1); const int j = k * (8 / hl);
;       const float2 wc = make_float2(c16(j), INV ? s16(j) : -s16(j));
;       const float2 tw = cmul(wb, wc);
;       if (!INV) { const float2 p = x[m], q = x[m + hl]; x[m] = make_float2(p.x + q.x, p.y + q.y); x[m + hl] = cmul(make_float2(p.x - q.x, p.y - q.y), tw); }
;       else { const float2 p = x[m], q = cmul(x[m + hl], tw); x[m] = make_float2(p.x + q.x, p.y + q.y); x[m + hl] = make_float2(p.x - q.x, p.y - q.y); }
;     }
; template <int LR>
; __device__ __forceinline__ void fft_first(float2* X, const bf16* __restrict__ u0, const bf16* __restrict__ u1, const int tid) {
;   constexpr int R = 1 << LR;
;   float2 x[R];
; #pragma unroll
;   for (int m = 0; m < R / 2; ++m) x[m] = make_float2(bfl(u0[tid + 512 * m]), bfl(u1[tid + 512 * m]));
; #pragma unroll
;   for (int m = R / 2; m < R; ++m) x[m] = make_float2(0.f, 0.f);
;   fft_stages<LR, false>(x, tid, 512);
; #pragma unroll
;   for (int m = 0; m < R; ++m) X[PIDX(tid + 512 * m)] = x[m];
;   __syncthreads();
; }
.LBB0_669:
	s_lshl_b32 s12, s18, 1
	s_lshl_b32 s12, s12, s20
	s_lshl_b32 s12, s12, 1
	s_add_u32 s40, s17, s12
	s_addc_u32 s41, s19, 0
	s_add_u32 s42, s40, s16
	s_addc_u32 s43, s41, 0
	s_mov_b64 s[12:13], -1
	s_and_b64 vcc, exec, s[10:11]
	s_cbranch_vccz .LBB0_671
	v_mov_b32_e32 v2, v208
	s_mov_b32 s12, s71
	v_ashrrev_i32_e32 v3, 31, v2
	v_lshlrev_b64 v[4:5], 1, v[2:3]
	v_lshl_add_u64 v[6:7], s[40:41], 0, v[4:5]
	v_lshl_add_u64 v[4:5], s[42:43], 0, v[4:5]
	s_nop 0
	s_nop 0
	v_cvt_f32_i32_e32 v8, v2
	v_add_u32_e32 v4, 0x400, v2
	v_add_u32_e32 v3, 0x200, v2
	v_add_u32_e32 v6, 0x600, v2
	v_ashrrev_i32_e32 v10, 4, v2
	v_lshl_add_u32 v12, v2, 3, 0
	v_add_u32_e32 v14, 0x800, v2
	v_add_u32_e32 v16, 0xa00, v2
	v_add_u32_e32 v17, 0xc00, v2
	v_add_u32_e32 v2, 0xe00, v2
	v_ashrrev_i32_e32 v4, 4, v4
	v_lshl_add_u32 v40, v10, 3, v12
	v_ashrrev_i32_e32 v3, 4, v3
	v_ashrrev_i32_e32 v6, 4, v6
	v_ashrrev_i32_e32 v10, 4, v14
	v_ashrrev_i32_e32 v14, 4, v16
	v_ashrrev_i32_e32 v16, 4, v17
	v_ashrrev_i32_e32 v2, 4, v2
	v_lshl_add_u32 v42, v4, 3, v12
	v_mul_f32_e32 v4, 0x3a000000, v8
	v_lshl_add_u32 v41, v3, 3, v12
	v_lshl_add_u32 v43, v6, 3, v12
	v_lshl_add_u32 v44, v10, 3, v12
	v_lshl_add_u32 v45, v14, 3, v12
	v_lshl_add_u32 v46, v16, 3, v12
	v_lshl_add_u32 v47, v2, 3, v12
	v_cos_f32_e32 v10, v4
	v_sin_f32_e32 v12, v4
	v_mul_f32_e32 v6, 0x3a800000, v8
	v_cos_f32_e32 v14, v6
	v_sin_f32_e32 v16, v6
	v_mul_f32_e32 v2, 0x39800000, v8
	v_fmamk_f32 v4, v12, 0x80000000, v10
	v_fma_f32 v6, v10, s91, -v12
	v_fma_f32 v8, v10, 0, -v12
	v_fma_f32 v10, v12, s91, -v10
	v_cos_f32_e32 v3, v2
	v_sin_f32_e32 v2, v2
	v_fmamk_f32 v12, v16, 0x80000000, v14
	v_fma_f32 v14, v14, s91, -v16
	s_mov_b32 s13, s70
	v_xor_b32_e32 v48, 0x80000000, v2
	v_pk_mov_b32 v[16:17], v[2:3], v[2:3] op_sel:[1,0]
	s_mov_b32 s90, s75
	v_mov_b32_e32 v17, v48
	v_fma_f32 v16, -v2, 0, v16
	v_fma_f32 v17, -v3, 0, v17
	v_lshlrev_b32_e32 v19, 16, v219
	v_lshlrev_b32_e32 v18, 16, v218
	v_lshlrev_b32_e32 v21, 16, v221
	v_lshlrev_b32_e32 v20, 16, v220
	v_lshlrev_b32_e32 v23, 16, v223
	v_lshlrev_b32_e32 v22, 16, v222
	v_lshlrev_b32_e32 v25, 16, v225
	v_lshlrev_b32_e32 v24, 16, v224
	s_cmp_eq_u32 s18, 3
	s_cbranch_scc1 .Lpf_skip_a
	s_lshl_b32 s57, s62, 1
	s_add_u32 s58, s58, s57
	s_addc_u32 s59, s59, 0
	s_add_u32 s60, s60, s57
	s_addc_u32 s61, s61, 0
	v_lshl_add_u64 v[234:235], s[58:59], 0, v[238:239]
	v_lshl_add_u64 v[236:237], s[60:61], 0, v[238:239]
	global_load_ushort v218, v[234:235], off
	global_load_ushort v219, v[236:237], off
	global_load_ushort v220, v[234:235], off offset:1024
	global_load_ushort v221, v[236:237], off offset:1024
	global_load_ushort v222, v[234:235], off offset:2048
	global_load_ushort v223, v[236:237], off offset:2048
	global_load_ushort v224, v[234:235], off offset:3072
	global_load_ushort v225, v[236:237], off offset:3072
.Lpf_skip_a:
	v_add_f32_e32 v26, 0, v18
	v_add_f32_e32 v27, 0, v19
	v_add_f32_e32 v28, 0, v20
	v_add_f32_e32 v29, 0, v21
	v_add_f32_e32 v30, 0, v22
	v_add_f32_e32 v31, 0, v23
	v_add_f32_e32 v32, 0, v24
	v_add_f32_e32 v33, 0, v25
	v_sub_f32_e32 v34, v26, v30
	v_sub_f32_e32 v35, v27, v31
	v_sub_f32_e32 v36, v28, v32
	v_sub_f32_e32 v37, v29, v33
	v_add_f32_e32 v26, v26, v30
	v_add_f32_e32 v27, v27, v31
	v_add_f32_e32 v28, v28, v32
	v_add_f32_e32 v29, v29, v33
	v_mul_f32_e32 v30, v6, v34
	v_mul_f32_e32 v31, v6, v35
	v_mul_f32_e32 v32, v10, v36
	v_mul_f32_e32 v33, v10, v37
	v_sub_f32_e32 v38, v26, v28
	v_sub_f32_e32 v39, v27, v29
	v_add_f32_e32 v26, v26, v28
	v_add_f32_e32 v27, v27, v29
	v_fma_f32 v28, v4, v34, -v31
	v_fma_f32 v29, v4, v35, v30
	v_fma_f32 v34, v8, v36, -v33
	v_fma_f32 v35, v8, v37, v32
	v_mul_f32_e32 v36, v14, v38
	v_mul_f32_e32 v37, v14, v39


; __device__ __forceinline__ float2 cmul(float2 a, float2 b) { return make_float2(a.x * b.x - a.y * b.y, a.x * b.y + a.y * b.x); }
; #define tid ltid()
; template <int LR, bool INV>
; __device__ __forceinline__ void fft_stages(float2 (&x)[1 << LR], const int r, const int s) {
;     ...
;   for (int st = 0; st < LR; ++st) {
;     const int hl = INV ? (1 << st) : (R >> (st + 1));
;     const float fb = (float)r * (0.5f / (float)(hl * s));
;     const float2 wb = make_float2(__builtin_amdgcn_cosf(fb), INV ? __builtin_amdgcn_sinf(fb) : -__builtin_amdgcn_sinf(fb));
; #pragma unroll
;     for (int m = 0; m < R; ++m) {
;       if (m & hl) continue;
;       const int k = m & (hl - 1); const int j = k * (8 / hl);
;       const float2 wc = make_float2(c16(j), INV ? s16(j) : -s16(j));
;       const float2 tw = cmul(wb, wc);
;       if (!INV) { const float2 p = x[m], q = x[m + hl]; x[m] = make_float2(p.x + q.x, p.y + q.y); x[m + hl] = cmul(make_float2(p.x - q.x, p.y - q.y), tw); }
;       else { const float2 p = x[m], q = cmul(x[m + hl], tw); x[m] = make_float2(p.x + q.x, p.y + q.y); x[m + hl] = make_float2(p.x - q.x, p.y - q.y); }
;     }
; template <int LR>
; __device__ __forceinline__ void fft_first(float2* X, const bf16* __restrict__ u0, const bf16* __restrict__ u1, const int tid) {
;     ...
;   for (int m = 0; m < R; ++m) X[PIDX(tid + 512 * m)] = x[m];
	ds_write_b64 v40, v[26:27]
	v_fma_f32 v26, v12, v38, -v37
	v_fma_f32 v27, v12, v39, v36
	v_sub_f32_e32 v32, v28, v34
	v_sub_f32_e32 v33, v29, v35

; __device__ __forceinline__ float2 cmul(float2 a, float2 b) { return make_float2(a.x * b.x - a.y * b.y, a.x * b.y + a.y * b.x); }
; #define tid ltid()
; template <int LR, bool INV>
; __device__ __forceinline__ void fft_stages(float2 (&x)[1 << LR], const int r, const int s) {
;     ...
;   for (int st = 0; st < LR; ++st) {
;     const int hl = INV ? (1 << st) : (R >> (st + 1));
;     const float fb = (float)r * (0.5f / (float)(hl * s));
;     const float2 wb = make_float2(__builtin_amdgcn_cosf(fb), INV ? __builtin_amdgcn_sinf(fb) : -__builtin_amdgcn_sinf(fb));
; #pragma unroll
;     for (int m = 0; m < R; ++m) {
;       if (m & hl) continue;
;       const int k = m & (hl - 1); const int j = k * (8 / hl);
;       const float2 wc = make_float2(c16(j), INV ? s16(j) : -s16(j));
;       const float2 tw = cmul(wb, wc);
;       if (!INV) { const float2 p = x[m], q = x[m + hl]; x[m] = make_float2(p.x + q.x, p.y + q.y); x[m + hl] = cmul(make_float2(p.x - q.x, p.y - q.y), tw); }
;       else { const float2 p = x[m], q = cmul(x[m + hl], tw); x[m] = make_float2(p.x + q.x, p.y + q.y); x[m + hl] = make_float2(p.x - q.x, p.y - q.y); }
;     }
; template <int LR>
; __device__ __forceinline__ void fft_first(float2* X, const bf16* __restrict__ u0, const bf16* __restrict__ u1, const int tid) {
;     ...
;   for (int m = 0; m < R; ++m) X[PIDX(tid + 512 * m)] = x[m];
	v_add_f32_e32 v28, v28, v34
	v_add_f32_e32 v29, v29, v35
	v_mul_f32_e32 v30, v14, v32
	v_mul_f32_e32 v31, v14, v33
	ds_write_b64 v41, v[26:27] offset:4096
	ds_write_b64 v42, v[28:29] offset:8192
	v_fma_f32 v26, v12, v32, -v31
	v_fma_f32 v27, v12, v33, v30

; __device__ __forceinline__ float2 cmul(float2 a, float2 b) { return make_float2(a.x * b.x - a.y * b.y, a.x * b.y + a.y * b.x); }
; #define tid ltid()
; template <int LR, bool INV>
; __device__ __forceinline__ void fft_stages(float2 (&x)[1 << LR], const int r, const int s) {
;     ...
;   for (int st = 0; st < LR; ++st) {
;     const int hl = INV ? (1 << st) : (R >> (st + 1));
;     const float fb = (float)r * (0.5f / (float)(hl * s));
;     const float2 wb = make_float2(__builtin_amdgcn_cosf(fb), INV ? __builtin_amdgcn_sinf(fb) : -__builtin_amdgcn_sinf(fb));
; #pragma unroll
;     for (int m = 0; m < R; ++m) {
;       if (m & hl) continue;
;       const int k = m & (hl - 1); const int j = k * (8 / hl);
;       const float2 wc = make_float2(c16(j), INV ? s16(j) : -s16(j));
;       const float2 tw = cmul(wb, wc);
;       if (!INV) { const float2 p = x[m], q = x[m + hl]; x[m] = make_float2(p.x + q.x, p.y + q.y); x[m + hl] = cmul(make_float2(p.x - q.x, p.y - q.y), tw); }
;       else { const float2 p = x[m], q = cmul(x[m + hl], tw); x[m] = make_float2(p.x + q.x, p.y + q.y); x[m + hl] = make_float2(p.x - q.x, p.y - q.y); }
;     }
; template <int LR>
; __device__ __forceinline__ void fft_first(float2* X, const bf16* __restrict__ u0, const bf16* __restrict__ u1, const int tid) {
;     ...
;   for (int m = 0; m < R; ++m) X[PIDX(tid + 512 * m)] = x[m];
	ds_write_b64 v43, v[26:27] offset:12288
	v_mov_b32_e32 v26, v19
	v_mul_f32_e32 v27, v16, v26
	v_mul_f32_e32 v26, v17, v26
	v_fma_f32 v28, v16, v18, -v26
	v_fma_f32 v29, v17, v18, v27
	v_mov_b32_e32 v26, v21

; __device__ __forceinline__ float2 cmul(float2 a, float2 b) { return make_float2(a.x * b.x - a.y * b.y, a.x * b.y + a.y * b.x); }
; template <int LR, bool INV>
; __device__ __forceinline__ void fft_stages(float2 (&x)[1 << LR], const int r, const int s) {
;     ...
;   for (int st = 0; st < LR; ++st) {
;     const int hl = INV ? (1 << st) : (R >> (st + 1));
;     const float fb = (float)r * (0.5f / (float)(hl * s));
;     const float2 wb = make_float2(__builtin_amdgcn_cosf(fb), INV ? __builtin_amdgcn_sinf(fb) : -__builtin_amdgcn_sinf(fb));
; #pragma unroll
;     for (int m = 0; m < R; ++m) {
;       if (m & hl) continue;
;       const int k = m & (hl - 1); const int j = k * (8 / hl);
;       const float2 wc = make_float2(c16(j), INV ? s16(j) : -s16(j));
;       const float2 tw = cmul(wb, wc);
	v_mul_f32_e32 v16, s70, v2
	v_mul_f32_e32 v17, s70, v3
	v_fma_f32 v18, v3, s12, v16
	v_fma_f32 v19, v2, s13, v17
	v_mul_f32_e32 v27, v18, v26
	v_mul_f32_e32 v26, v19, v26
	v_fma_f32 v30, v18, v20, -v26
	v_fma_f32 v31, v19, v20, v27
	v_mov_b32_e32 v20, v23

; __device__ __forceinline__ float2 cmul(float2 a, float2 b) { return make_float2(a.x * b.x - a.y * b.y, a.x * b.y + a.y * b.x); }
; template <int LR, bool INV>
; __device__ __forceinline__ void fft_stages(float2 (&x)[1 << LR], const int r, const int s) {
;     ...
;   for (int st = 0; st < LR; ++st) {
;     const int hl = INV ? (1 << st) : (R >> (st + 1));
;     const float fb = (float)r * (0.5f / (float)(hl * s));
;     const float2 wb = make_float2(__builtin_amdgcn_cosf(fb), INV ? __builtin_amdgcn_sinf(fb) : -__builtin_amdgcn_sinf(fb));
; #pragma unroll
;     for (int m = 0; m < R; ++m) {
;       if (m & hl) continue;
;       const int k = m & (hl - 1); const int j = k * (8 / hl);
;       const float2 wc = make_float2(c16(j), INV ? s16(j) : -s16(j));
;       const float2 tw = cmul(wb, wc);
	v_fma_f32 v18, v3, s90, -v2
	v_fma_f32 v19, v2, s91, -v3
	v_mul_f32_e32 v21, v18, v20
	v_mul_f32_e32 v20, v19, v20
	v_pk_fma_f32 v[2:3], v[2:3], s[70:71], v[16:17] op_sel:[1,0,0] op_sel_hi:[0,1,1]
	v_mov_b32_e32 v16, v25
	v_fma_f32 v26, v18, v22, -v20
	v_fma_f32 v27, v19, v22, v21
	v_mul_f32_e32 v17, v2, v16
	v_mul_f32_e32 v16, v3, v16

; __device__ __forceinline__ float2 cmul(float2 a, float2 b) { return make_float2(a.x * b.x - a.y * b.y, a.x * b.y + a.y * b.x); }
; template <int LR, bool INV>
; __device__ __forceinline__ void fft_stages(float2 (&x)[1 << LR], const int r, const int s) {
;     ...
;       const float2 tw = cmul(wb, wc);
;       if (!INV) { const float2 p = x[m], q = x[m + hl]; x[m] = make_float2(p.x + q.x, p.y + q.y); x[m + hl] = cmul(make_float2(p.x - q.x, p.y - q.y), tw); }
	v_fma_f32 v18, v2, v24, -v16
	v_fma_f32 v19, v3, v24, v17
	s_mov_b64 s[12:13], 0

; __device__ __forceinline__ float2 cmul(float2 a, float2 b) { return make_float2(a.x * b.x - a.y * b.y, a.x * b.y + a.y * b.x); }
; template <int LR, bool INV>
; __device__ __forceinline__ void fft_stages(float2 (&x)[1 << LR], const int r, const int s) {
;     ...
;       if (!INV) { const float2 p = x[m], q = x[m + hl]; x[m] = make_float2(p.x + q.x, p.y + q.y); x[m + hl] = cmul(make_float2(p.x - q.x, p.y - q.y), tw); }
	v_sub_f32_e32 v2, v28, v26
	v_sub_f32_e32 v3, v29, v27
	v_mul_f32_e32 v7, v6, v3
	v_mul_f32_e32 v6, v6, v2
	v_fma_f32 v16, v4, v2, -v7
	v_fma_f32 v17, v4, v3, v6

; __device__ __forceinline__ float2 cmul(float2 a, float2 b) { return make_float2(a.x * b.x - a.y * b.y, a.x * b.y + a.y * b.x); }
; template <int LR, bool INV>
; __device__ __forceinline__ void fft_stages(float2 (&x)[1 << LR], const int r, const int s) {
;     ...
;       if (!INV) { const float2 p = x[m], q = x[m + hl]; x[m] = make_float2(p.x + q.x, p.y + q.y); x[m + hl] = cmul(make_float2(p.x - q.x, p.y - q.y), tw); }
	v_sub_f32_e32 v2, v30, v18
	v_sub_f32_e32 v3, v31, v19
	v_mul_f32_e32 v4, v10, v2
	v_mul_f32_e32 v5, v10, v3
	v_fma_f32 v6, v8, v2, -v5
	v_fma_f32 v7, v8, v3, v4

; __device__ __forceinline__ float2 cmul(float2 a, float2 b) { return make_float2(a.x * b.x - a.y * b.y, a.x * b.y + a.y * b.x); }
; template <int LR, bool INV>
; __device__ __forceinline__ void fft_stages(float2 (&x)[1 << LR], const int r, const int s) {
;   constexpr int R = 1 << LR;
; #pragma unroll
;   for (int st = 0; st < LR; ++st) {
;     const int hl = INV ? (1 << st) : (R >> (st + 1));
;     const float fb = (float)r * (0.5f / (float)(hl * s));
;     const float2 wb = make_float2(__builtin_amdgcn_cosf(fb), INV ? __builtin_amdgcn_sinf(fb) : -__builtin_amdgcn_sinf(fb));
; #pragma unroll
;     for (int m = 0; m < R; ++m) {
;       if (m & hl) continue;
;       const int k = m & (hl - 1); const int j = k * (8 / hl);
;       const float2 wc = make_float2(c16(j), INV ? s16(j) : -s16(j));
;       const float2 tw = cmul(wb, wc);
;       if (!INV) { const float2 p = x[m], q = x[m + hl]; x[m] = make_float2(p.x + q.x, p.y + q.y); x[m + hl] = cmul(make_float2(p.x - q.x, p.y - q.y), tw); }
;       else { const float2 p = x[m], q = cmul(x[m + hl], tw); x[m] = make_float2(p.x + q.x, p.y + q.y); x[m + hl] = make_float2(p.x - q.x, p.y - q.y); }
;     }
;   }
	v_sub_f32_e32 v2, v16, v6
	v_sub_f32_e32 v3, v17, v7
	v_mul_f32_e32 v4, v14, v2
	v_mul_f32_e32 v5, v14, v3
	v_fma_f32 v8, v12, v2, -v5
	v_fma_f32 v9, v12, v3, v4

; __device__ __forceinline__ float bfl(unsigned w) { return __uint_as_float(w << 16); }
; __device__ __forceinline__ float2 cmul(float2 a, float2 b) { return make_float2(a.x * b.x - a.y * b.y, a.x * b.y + a.y * b.x); }
; #define tid ltid()
; template <int LR, bool INV>
; __device__ __forceinline__ void fft_stages(float2 (&x)[1 << LR], const int r, const int s) {
;   constexpr int R = 1 << LR;
; #pragma unroll
;   for (int st = 0; st < LR; ++st) {
;     const int hl = INV ? (1 << st) : (R >> (st + 1));
;     const float fb = (float)r * (0.5f / (float)(hl * s));
;     const float2 wb = make_float2(__builtin_amdgcn_cosf(fb), INV ? __builtin_amdgcn_sinf(fb) : -__builtin_amdgcn_sinf(fb));
; #pragma unroll
;     for (int m = 0; m < R; ++m) {
;       if (m & hl) continue;
;       const int k = m & (hl - 1); const int j = k * (8 / hl);
;       const float2 wc = make_float2(c16(j), INV ? s16(j) : -s16(j));
;       const float2 tw = cmul(wb, wc);
;       if (!INV) { const float2 p = x[m], q = x[m + hl]; x[m] = make_float2(p.x + q.x, p.y + q.y); x[m + hl] = cmul(make_float2(p.x - q.x, p.y - q.y), tw); }
;       else { const float2 p = x[m], q = cmul(x[m + hl], tw); x[m] = make_float2(p.x + q.x, p.y + q.y); x[m + hl] = make_float2(p.x - q.x, p.y - q.y); }
;     }
;   }
; template <int LR>
; __device__ __forceinline__ void fft_first(float2* X, const bf16* __restrict__ u0, const bf16* __restrict__ u1, const int tid) {
;   constexpr int R = 1 << LR;
;   float2 x[R];
; #pragma unroll
;   for (int m = 0; m < R / 2; ++m) x[m] = make_float2(bfl(u0[tid + 512 * m]), bfl(u1[tid + 512 * m]));
; #pragma unroll
;   for (int m = R / 2; m < R; ++m) x[m] = make_float2(0.f, 0.f);
;   fft_stages<LR, false>(x, tid, 512);
; #pragma unroll
;   for (int m = 0; m < R; ++m) X[PIDX(tid + 512 * m)] = x[m];
;   __syncthreads();
	v_add_f32_e32 v2, v28, v26
	v_add_f32_e32 v3, v29, v27
	v_add_f32_e32 v4, v30, v18
	v_add_f32_e32 v5, v31, v19
	v_sub_f32_e32 v10, v2, v4
	v_sub_f32_e32 v11, v3, v5
	v_add_f32_e32 v2, v2, v4
	v_add_f32_e32 v3, v3, v5
	v_mul_f32_e32 v15, v14, v11
	v_mul_f32_e32 v14, v14, v10
	v_fma_f32 v18, v12, v10, -v15
	v_fma_f32 v11, v12, v11, v14
	v_mov_b32_e32 v19, v11
	ds_write_b64 v44, v[2:3] offset:16384
	ds_write_b64 v45, v[18:19] offset:20480
	v_add_f32_e32 v2, v16, v6
	v_add_f32_e32 v3, v17, v7
	ds_write_b64 v46, v[2:3] offset:24576
	ds_write_b64 v47, v[8:9] offset:28672
	s_waitcnt lgkmcnt(0)
	s_barrier
.LBB0_671:
	s_andn2_b64 vcc, exec, s[12:13]
	s_cbranch_vccnz .LBB0_673
	v_mov_b32_e32 v2, v208
	s_mov_b32 s14, s71
	v_ashrrev_i32_e32 v3, 31, v2
	v_lshlrev_b64 v[4:5], 1, v[2:3]
	v_lshl_add_u64 v[6:7], s[40:41], 0, v[4:5]
	v_lshl_add_u64 v[4:5], s[42:43], 0, v[4:5]
	v_add_co_u32_e32 v6, vcc, s64, v6
	v_cvt_f32_i32_e32 v64, v2
	s_nop 0
	v_addc_co_u32_e32 v7, vcc, 0, v7, vcc
	v_add_co_u32_e32 v4, vcc, s64, v4
	s_mov_b32 s15, s70
	s_nop 0
	v_addc_co_u32_e32 v5, vcc, 0, v5, vcc
	v_mul_f32_e32 v4, 0x39000000, v64
	v_sin_f32_e32 v9, v4
	v_cos_f32_e32 v8, v4
	v_mul_f32_e32 v53, 0x39800000, v64
	s_mov_b32 s90, s75
	v_xor_b32_e32 v5, 0x80000000, v9
	v_mul_f32_e32 v10, 0, v9
	v_mov_b32_e32 v4, v8
	v_mul_f32_e32 v11, 0, v8
	v_mov_b32_e32 v36, v9
	v_mov_b32_e32 v37, v8
	s_mov_b32 s12, s71
	v_cos_f32_e32 v29, v53
	v_mul_f32_e32 v13, 0xbf3504f3, v9
	v_mul_f32_e32 v12, 0x3f3504f3, v8
	v_sub_f32_e32 v22, v4, v10
	v_sub_f32_e32 v23, v5, v11
	v_mul_f32_e32 v4, s14, v36
	v_mul_f32_e32 v5, s15, v37
	v_mul_f32_e32 v10, s94, v36
	v_mul_f32_e32 v11, s94, v37
	v_mul_f32_e32 v38, s72, v36
	v_mul_f32_e32 v39, s73, v37
	v_fma_f32 v6, v8, s90, -v9
	v_fma_f32 v7, v9, s91, -v8
	v_mul_f32_e32 v32, 0xbec3ef15, v8
	v_mul_f32_e32 v41, s72, v8
	v_fma_f32 v14, -v36, s12, v12
	v_fma_f32 v15, -v37, s12, v13
	v_pk_fma_f32 v[4:5], v[36:37], s[12:13], v[4:5] op_sel:[0,0,1] op_sel_hi:[1,0,0] neg_lo:[1,0,0] neg_hi:[1,0,0]
	v_fma_f32 v24, v8, s72, -v10
	v_fma_f32 v25, v9, s73, -v11
	v_pk_mov_b32 v[42:43], v[10:11], v[10:11] op_sel:[1,0]

; __device__ __forceinline__ float bfl(unsigned w) { return __uint_as_float(w << 16); }
; __device__ __forceinline__ float2 cmul(float2 a, float2 b) { return make_float2(a.x * b.x - a.y * b.y, a.x * b.y + a.y * b.x); }
; #define tid ltid()
; template <int LR, bool INV>
; __device__ __forceinline__ void fft_stages(float2 (&x)[1 << LR], const int r, const int s) {
;   constexpr int R = 1 << LR;
; #pragma unroll
;   for (int st = 0; st < LR; ++st) {
;     const int hl = INV ? (1 << st) : (R >> (st + 1));
;     const float fb = (float)r * (0.5f / (float)(hl * s));
;     const float2 wb = make_float2(__builtin_amdgcn_cosf(fb), INV ? __builtin_amdgcn_sinf(fb) : -__builtin_amdgcn_sinf(fb));
; #pragma unroll
;     for (int m = 0; m < R; ++m) {
;       if (m & hl) continue;
;       const int k = m & (hl - 1); const int j = k * (8 / hl);
;       const float2 wc = make_float2(c16(j), INV ? s16(j) : -s16(j));
;       const float2 tw = cmul(wb, wc);
;       if (!INV) { const float2 p = x[m], q = x[m + hl]; x[m] = make_float2(p.x + q.x, p.y + q.y); x[m + hl] = cmul(make_float2(p.x - q.x, p.y - q.y), tw); }
;       else { const float2 p = x[m], q = cmul(x[m + hl], tw); x[m] = make_float2(p.x + q.x, p.y + q.y); x[m + hl] = make_float2(p.x - q.x, p.y - q.y); }
;     }
;   }
; template <int LR>
; __device__ __forceinline__ void fft_first(float2* X, const bf16* __restrict__ u0, const bf16* __restrict__ u1, const int tid) {
;     ...
;   for (int m = 0; m < R / 2; ++m) x[m] = make_float2(bfl(u0[tid + 512 * m]), bfl(u1[tid + 512 * m]));
; #pragma unroll
;   for (int m = R / 2; m < R; ++m) x[m] = make_float2(0.f, 0.f);
	v_mov_b32_e32 v40, v38
	v_add_u32_e32 v60, 0x200, v2
	v_add_u32_e32 v61, 0x400, v2
	v_mul_f32_e32 v17, 0xbec3ef15, v9
	v_mov_b32_e32 v16, v42
	v_sub_f32_e32 v16, v16, v40
	v_sub_f32_e32 v17, v17, v41
	v_add_u32_e32 v62, 0x600, v2
	v_add_u32_e32 v63, 0x800, v2
	v_add_u32_e32 v65, 0xa00, v2
	v_add_u32_e32 v67, 0xe00, v2
	v_add_u32_e32 v66, 0xc00, v2
	v_lshlrev_b32_e32 v34, 16, v218
	v_mul_f32_e32 v3, 0x3a000000, v64
	v_lshlrev_b32_e32 v30, 16, v220
	v_lshlrev_b32_e32 v31, 16, v221
	v_lshlrev_b32_e32 v26, 16, v222
	v_lshlrev_b32_e32 v27, 16, v223
	v_sin_f32_e32 v28, v53
	v_lshlrev_b32_e32 v21, 16, v225
	v_mov_b32_e32 v33, v43
	v_lshlrev_b32_e32 v35, 16, v219
	v_sub_f32_e32 v54, v32, v40
	v_sub_f32_e32 v55, v33, v41
	v_lshlrev_b32_e32 v18, 16, v226
	v_lshlrev_b32_e32 v19, 16, v227
	v_mov_b32_e32 v32, v29
	v_mov_b32_e32 v33, v28
	v_mul_f32_e32 v58, s70, v32
	v_mul_f32_e32 v59, s71, v33
	v_ashrrev_i32_e32 v33, 4, v60
	v_add_f32_e32 v68, 0, v18
	v_add_f32_e32 v69, 0, v19
	v_lshlrev_b32_e32 v8, 16, v232
	v_fma_f32 v52, -v36, s94, v39
	v_fma_f32 v53, -v37, s94, v38
	v_cos_f32_e32 v37, v3
	v_sin_f32_e32 v3, v3
	v_lshlrev_b32_e32 v20, 16, v224
	v_lshlrev_b32_e32 v13, 16, v229
	v_lshlrev_b32_e32 v11, 16, v231
	v_fmamk_f32 v36, v3, 0x80000000, v37
	v_fma_f32 v42, v37, s91, -v3
	v_fma_f32 v38, v37, 0, -v3
	v_fma_f32 v40, v3, s91, -v37
	v_ashrrev_i32_e32 v37, 4, v61
	v_add_f32_e32 v60, 0, v34
	v_add_f32_e32 v61, 0, v35
	v_fmamk_f32 v48, v28, 0x80000000, v29
	v_fma_f32 v50, v29, s91, -v28
	v_mul_f32_e32 v56, s70, v28
	v_mul_f32_e32 v57, s71, v29
	v_fma_f32 v44, v29, 0, -v28
	v_fma_f32 v46, v28, s91, -v29
	v_mul_f32_e32 v28, 0x3a800000, v64
	v_sub_f32_e32 v76, v60, v68
	v_sub_f32_e32 v77, v61, v69
	v_lshlrev_b32_e32 v12, 16, v228
	v_cos_f32_e32 v29, v28
	v_sin_f32_e32 v32, v28
	v_mul_f32_e32 v78, v50, v76
	v_mul_f32_e32 v79, v50, v77
	v_ashrrev_i32_e32 v39, 4, v62
	v_ashrrev_i32_e32 v41, 4, v63
	v_add_f32_e32 v62, 0, v30
	v_add_f32_e32 v63, 0, v31
	v_add_f32_e32 v70, 0, v12
	v_add_f32_e32 v71, 0, v13
	v_fma_f32 v80, v48, v76, -v79
	v_fma_f32 v81, v48, v77, v78

; __device__ __forceinline__ float2 cmul(float2 a, float2 b) { return make_float2(a.x * b.x - a.y * b.y, a.x * b.y + a.y * b.x); }
; template <int LR, bool INV>
; __device__ __forceinline__ void fft_stages(float2 (&x)[1 << LR], const int r, const int s) {
;   constexpr int R = 1 << LR;
; #pragma unroll
;   for (int st = 0; st < LR; ++st) {
;     const int hl = INV ? (1 << st) : (R >> (st + 1));
;     const float fb = (float)r * (0.5f / (float)(hl * s));
;     const float2 wb = make_float2(__builtin_amdgcn_cosf(fb), INV ? __builtin_amdgcn_sinf(fb) : -__builtin_amdgcn_sinf(fb));
; #pragma unroll
;     for (int m = 0; m < R; ++m) {
;       if (m & hl) continue;
;       const int k = m & (hl - 1); const int j = k * (8 / hl);
;       const float2 wc = make_float2(c16(j), INV ? s16(j) : -s16(j));
;       const float2 tw = cmul(wb, wc);
;       if (!INV) { const float2 p = x[m], q = x[m + hl]; x[m] = make_float2(p.x + q.x, p.y + q.y); x[m + hl] = cmul(make_float2(p.x - q.x, p.y - q.y), tw); }
;       else { const float2 p = x[m], q = cmul(x[m + hl], tw); x[m] = make_float2(p.x + q.x, p.y + q.y); x[m + hl] = make_float2(p.x - q.x, p.y - q.y); }
;     }
;   }
	v_sub_f32_e32 v76, v62, v70
	v_sub_f32_e32 v77, v63, v71
	v_sub_f32_e32 v78, v56, v57
	v_sub_f32_e32 v79, v56, v57
	v_lshlrev_b32_e32 v10, 16, v230
	v_mul_f32_e32 v82, v78, v76
	v_mul_f32_e32 v83, v79, v77
	v_sub_f32_e32 v56, v57, v59
	v_fmamk_f32 v28, v32, 0x80000000, v29
	v_fma_f32 v32, v29, s91, -v32
	v_lshl_add_u32 v29, v2, 3, 0
	v_ashrrev_i32_e32 v43, 4, v65
	v_ashrrev_i32_e32 v47, 4, v67
	v_add_f32_e32 v64, 0, v26
	v_add_f32_e32 v65, 0, v27
	v_add_f32_e32 v72, 0, v10
	v_add_f32_e32 v73, 0, v11
	v_fma_f32 v84, v56, v76, -v83
	v_fma_f32 v85, v56, v77, v82
	v_ashrrev_i32_e32 v45, 4, v66
	v_lshl_add_u32 v47, v47, 3, v29

; __device__ __forceinline__ float bfl(unsigned w) { return __uint_as_float(w << 16); }
; __device__ __forceinline__ float2 cmul(float2 a, float2 b) { return make_float2(a.x * b.x - a.y * b.y, a.x * b.y + a.y * b.x); }
; #define tid ltid()
; template <int LR, bool INV>
; __device__ __forceinline__ void fft_stages(float2 (&x)[1 << LR], const int r, const int s) {
;   constexpr int R = 1 << LR;
; #pragma unroll
;   for (int st = 0; st < LR; ++st) {
;     const int hl = INV ? (1 << st) : (R >> (st + 1));
;     const float fb = (float)r * (0.5f / (float)(hl * s));
;     const float2 wb = make_float2(__builtin_amdgcn_cosf(fb), INV ? __builtin_amdgcn_sinf(fb) : -__builtin_amdgcn_sinf(fb));
; #pragma unroll
;     for (int m = 0; m < R; ++m) {
;       if (m & hl) continue;
;       const int k = m & (hl - 1); const int j = k * (8 / hl);
;       const float2 wc = make_float2(c16(j), INV ? s16(j) : -s16(j));
;       const float2 tw = cmul(wb, wc);
;       if (!INV) { const float2 p = x[m], q = x[m + hl]; x[m] = make_float2(p.x + q.x, p.y + q.y); x[m + hl] = cmul(make_float2(p.x - q.x, p.y - q.y), tw); }
;       else { const float2 p = x[m], q = cmul(x[m + hl], tw); x[m] = make_float2(p.x + q.x, p.y + q.y); x[m + hl] = make_float2(p.x - q.x, p.y - q.y); }
;     }
;   }
; template <int LR>
; __device__ __forceinline__ void fft_first(float2* X, const bf16* __restrict__ u0, const bf16* __restrict__ u1, const int tid) {
;     ...
;   for (int m = 0; m < R / 2; ++m) x[m] = make_float2(bfl(u0[tid + 512 * m]), bfl(u1[tid + 512 * m]));
; __global__ void __launch_bounds__(NTHR, 2) mega_fwd(Args a_unused) {
;     ...
;           for (int pr = 0; pr < 4; ++pr) {
;             bf16* u0 = urow + (size_t)(2 * pr) * L; bf16* u1 = u0 + L;
;             if (gsel) fft_first<4>(A, u0, u1, tid); else fft_first<3>(A, u0, u1, tid);
	v_sub_f32_e32 v76, v64, v72
	v_sub_f32_e32 v77, v65, v73
	v_lshlrev_b32_e32 v9, 16, v233
	s_cmp_eq_u32 s18, 3
	s_cbranch_scc1 .Lpf_skip_b
	s_lshl_b32 s57, s62, 1
	s_add_u32 s58, s58, s57
	s_addc_u32 s59, s59, 0
	s_add_u32 s60, s60, s57
	s_addc_u32 s61, s61, 0
	v_lshl_add_u64 v[234:235], s[58:59], 0, v[238:239]
	v_lshl_add_u64 v[236:237], s[60:61], 0, v[238:239]
	global_load_ushort v218, v[234:235], off
	global_load_ushort v219, v[236:237], off
	global_load_ushort v220, v[234:235], off offset:1024
	global_load_ushort v221, v[236:237], off offset:1024
	global_load_ushort v222, v[234:235], off offset:2048
	global_load_ushort v223, v[236:237], off offset:2048
	global_load_ushort v224, v[234:235], off offset:3072
	global_load_ushort v225, v[236:237], off offset:3072
	s_mov_b64 s[96:97], 0x1000
	v_lshl_add_u64 v[234:235], v[234:235], 0, s[96:97]
	v_lshl_add_u64 v[236:237], v[236:237], 0, s[96:97]
	global_load_ushort v226, v[234:235], off
	global_load_ushort v227, v[236:237], off
	global_load_ushort v228, v[234:235], off offset:1024
	global_load_ushort v229, v[236:237], off offset:1024
	global_load_ushort v230, v[234:235], off offset:2048
	global_load_ushort v231, v[236:237], off offset:2048
	global_load_ushort v232, v[234:235], off offset:3072
	global_load_ushort v233, v[236:237], off offset:3072
.Lpf_skip_b:
	v_lshl_add_u32 v45, v45, 3, v29
	v_mul_f32_e32 v82, v46, v76
	v_mul_f32_e32 v83, v46, v77
	v_add_f32_e32 v66, 0, v20
	v_add_f32_e32 v67, 0, v21
	v_add_f32_e32 v74, 0, v8
	v_add_f32_e32 v75, 0, v9
	v_fma_f32 v86, v44, v76, -v83
	v_fma_f32 v87, v44, v77, v82

; __device__ __forceinline__ float2 cmul(float2 a, float2 b) { return make_float2(a.x * b.x - a.y * b.y, a.x * b.y + a.y * b.x); }
; template <int LR, bool INV>
; __device__ __forceinline__ void fft_stages(float2 (&x)[1 << LR], const int r, const int s) {
;   constexpr int R = 1 << LR;
; #pragma unroll
;   for (int st = 0; st < LR; ++st) {
;     const int hl = INV ? (1 << st) : (R >> (st + 1));
;     const float fb = (float)r * (0.5f / (float)(hl * s));
;     const float2 wb = make_float2(__builtin_amdgcn_cosf(fb), INV ? __builtin_amdgcn_sinf(fb) : -__builtin_amdgcn_sinf(fb));
; #pragma unroll
;     for (int m = 0; m < R; ++m) {
;       if (m & hl) continue;
;       const int k = m & (hl - 1); const int j = k * (8 / hl);
;       const float2 wc = make_float2(c16(j), INV ? s16(j) : -s16(j));
;       const float2 tw = cmul(wb, wc);
;       if (!INV) { const float2 p = x[m], q = x[m + hl]; x[m] = make_float2(p.x + q.x, p.y + q.y); x[m + hl] = cmul(make_float2(p.x - q.x, p.y - q.y), tw); }
;       else { const float2 p = x[m], q = cmul(x[m + hl], tw); x[m] = make_float2(p.x + q.x, p.y + q.y); x[m + hl] = make_float2(p.x - q.x, p.y - q.y); }
;     }
;   }
	v_sub_f32_e32 v76, v66, v74
	v_sub_f32_e32 v77, v67, v75
	v_sub_f32_e32 v82, v59, v57
	v_mul_f32_e32 v88, v82, v76
	v_mul_f32_e32 v89, v82, v77
	v_pk_add_f32 v[58:59], v[58:59], v[58:59] op_sel:[0,1] op_sel_hi:[0,1] neg_lo:[0,1] neg_hi:[0,1]
	v_fma_f32 v90, v58, v76, -v89
	v_fma_f32 v91, v59, v77, v88
	v_lshl_add_u32 v43, v43, 3, v29

; __device__ __forceinline__ float2 cmul(float2 a, float2 b) { return make_float2(a.x * b.x - a.y * b.y, a.x * b.y + a.y * b.x); }
; template <int LR, bool INV>
; __device__ __forceinline__ void fft_stages(float2 (&x)[1 << LR], const int r, const int s) {
;   constexpr int R = 1 << LR;
; #pragma unroll
;   for (int st = 0; st < LR; ++st) {
;     const int hl = INV ? (1 << st) : (R >> (st + 1));
;     const float fb = (float)r * (0.5f / (float)(hl * s));
;     const float2 wb = make_float2(__builtin_amdgcn_cosf(fb), INV ? __builtin_amdgcn_sinf(fb) : -__builtin_amdgcn_sinf(fb));
; #pragma unroll
;     for (int m = 0; m < R; ++m) {
;       if (m & hl) continue;
;       const int k = m & (hl - 1); const int j = k * (8 / hl);
;       const float2 wc = make_float2(c16(j), INV ? s16(j) : -s16(j));
;       const float2 tw = cmul(wb, wc);
;       if (!INV) { const float2 p = x[m], q = x[m + hl]; x[m] = make_float2(p.x + q.x, p.y + q.y); x[m + hl] = cmul(make_float2(p.x - q.x, p.y - q.y), tw); }
;       else { const float2 p = x[m], q = cmul(x[m + hl], tw); x[m] = make_float2(p.x + q.x, p.y + q.y); x[m + hl] = make_float2(p.x - q.x, p.y - q.y); }
;     }
;   }
	v_sub_f32_e32 v76, v80, v86
	v_sub_f32_e32 v77, v81, v87
	v_add_f32_e32 v60, v60, v68
	v_add_f32_e32 v61, v61, v69
	v_add_f32_e32 v64, v64, v72
	v_add_f32_e32 v65, v65, v73
	v_lshl_add_u32 v37, v37, 3, v29
	v_mul_f32_e32 v88, v42, v76
	v_mul_f32_e32 v89, v42, v77
	v_sub_f32_e32 v68, v60, v64
	v_sub_f32_e32 v69, v61, v65
	v_fma_f32 v92, v36, v76, -v89
	v_fma_f32 v93, v36, v77, v88
	v_add_f32_e32 v62, v62, v70
	v_add_f32_e32 v63, v63, v71
	v_mul_f32_e32 v70, v42, v68
	v_mul_f32_e32 v71, v42, v69
	v_lshl_add_u32 v41, v41, 3, v29

; __device__ __forceinline__ float2 cmul(float2 a, float2 b) { return make_float2(a.x * b.x - a.y * b.y, a.x * b.y + a.y * b.x); }
; template <int LR, bool INV>
; __device__ __forceinline__ void fft_stages(float2 (&x)[1 << LR], const int r, const int s) {
;   constexpr int R = 1 << LR;
; #pragma unroll
;   for (int st = 0; st < LR; ++st) {
;     const int hl = INV ? (1 << st) : (R >> (st + 1));
;     const float fb = (float)r * (0.5f / (float)(hl * s));
;     const float2 wb = make_float2(__builtin_amdgcn_cosf(fb), INV ? __builtin_amdgcn_sinf(fb) : -__builtin_amdgcn_sinf(fb));
; #pragma unroll
;     for (int m = 0; m < R; ++m) {
;       if (m & hl) continue;
;       const int k = m & (hl - 1); const int j = k * (8 / hl);
;       const float2 wc = make_float2(c16(j), INV ? s16(j) : -s16(j));
;       const float2 tw = cmul(wb, wc);
;       if (!INV) { const float2 p = x[m], q = x[m + hl]; x[m] = make_float2(p.x + q.x, p.y + q.y); x[m + hl] = cmul(make_float2(p.x - q.x, p.y - q.y), tw); }
;       else { const float2 p = x[m], q = cmul(x[m + hl], tw); x[m] = make_float2(p.x + q.x, p.y + q.y); x[m + hl] = make_float2(p.x - q.x, p.y - q.y); }
;     }
;   }
	v_sub_f32_e32 v76, v84, v90
	v_sub_f32_e32 v77, v85, v91
	v_add_f32_e32 v66, v66, v74
	v_add_f32_e32 v67, v67, v75
	v_fma_f32 v72, v36, v68, -v71
	v_fma_f32 v73, v36, v69, v70
	v_lshl_add_u32 v39, v39, 3, v29
	v_mul_f32_e32 v88, v40, v76
	v_mul_f32_e32 v89, v40, v77

; __device__ __forceinline__ float2 cmul(float2 a, float2 b) { return make_float2(a.x * b.x - a.y * b.y, a.x * b.y + a.y * b.x); }
; template <int LR, bool INV>
; __device__ __forceinline__ void fft_stages(float2 (&x)[1 << LR], const int r, const int s) {
;   constexpr int R = 1 << LR;
; #pragma unroll
;   for (int st = 0; st < LR; ++st) {
;     const int hl = INV ? (1 << st) : (R >> (st + 1));
;     const float fb = (float)r * (0.5f / (float)(hl * s));
;     const float2 wb = make_float2(__builtin_amdgcn_cosf(fb), INV ? __builtin_amdgcn_sinf(fb) : -__builtin_amdgcn_sinf(fb));
; #pragma unroll
;     for (int m = 0; m < R; ++m) {
;       if (m & hl) continue;
;       const int k = m & (hl - 1); const int j = k * (8 / hl);
;       const float2 wc = make_float2(c16(j), INV ? s16(j) : -s16(j));
;       const float2 tw = cmul(wb, wc);
;       if (!INV) { const float2 p = x[m], q = x[m + hl]; x[m] = make_float2(p.x + q.x, p.y + q.y); x[m + hl] = cmul(make_float2(p.x - q.x, p.y - q.y), tw); }
;       else { const float2 p = x[m], q = cmul(x[m + hl], tw); x[m] = make_float2(p.x + q.x, p.y + q.y); x[m + hl] = make_float2(p.x - q.x, p.y - q.y); }
;     }
;   }
	v_sub_f32_e32 v68, v62, v66
	v_sub_f32_e32 v69, v63, v67
	v_fma_f32 v94, v38, v76, -v89
	v_fma_f32 v95, v38, v77, v88
	v_mul_f32_e32 v70, v40, v68
	v_mul_f32_e32 v71, v40, v69

; __device__ __forceinline__ float2 cmul(float2 a, float2 b) { return make_float2(a.x * b.x - a.y * b.y, a.x * b.y + a.y * b.x); }
; template <int LR, bool INV>
; __device__ __forceinline__ void fft_stages(float2 (&x)[1 << LR], const int r, const int s) {
;   constexpr int R = 1 << LR;
; #pragma unroll
;   for (int st = 0; st < LR; ++st) {
;     const int hl = INV ? (1 << st) : (R >> (st + 1));
;     const float fb = (float)r * (0.5f / (float)(hl * s));
;     const float2 wb = make_float2(__builtin_amdgcn_cosf(fb), INV ? __builtin_amdgcn_sinf(fb) : -__builtin_amdgcn_sinf(fb));
; #pragma unroll
;     for (int m = 0; m < R; ++m) {
;       if (m & hl) continue;
;       const int k = m & (hl - 1); const int j = k * (8 / hl);
;       const float2 wc = make_float2(c16(j), INV ? s16(j) : -s16(j));
;       const float2 tw = cmul(wb, wc);
;       if (!INV) { const float2 p = x[m], q = x[m + hl]; x[m] = make_float2(p.x + q.x, p.y + q.y); x[m + hl] = cmul(make_float2(p.x - q.x, p.y - q.y), tw); }
;       else { const float2 p = x[m], q = cmul(x[m + hl], tw); x[m] = make_float2(p.x + q.x, p.y + q.y); x[m + hl] = make_float2(p.x - q.x, p.y - q.y); }
;     }
;   }
	v_fma_f32 v74, v38, v68, -v71
	v_fma_f32 v75, v38, v69, v70
	v_lshl_add_u32 v33, v33, 3, v29
	v_sub_f32_e32 v76, v92, v94
	v_sub_f32_e32 v77, v93, v95

; __device__ __forceinline__ float2 cmul(float2 a, float2 b) { return make_float2(a.x * b.x - a.y * b.y, a.x * b.y + a.y * b.x); }
; template <int LR, bool INV>
; __device__ __forceinline__ void fft_stages(float2 (&x)[1 << LR], const int r, const int s) {
;   constexpr int R = 1 << LR;
; #pragma unroll
;   for (int st = 0; st < LR; ++st) {
;     const int hl = INV ? (1 << st) : (R >> (st + 1));
;     const float fb = (float)r * (0.5f / (float)(hl * s));
;     const float2 wb = make_float2(__builtin_amdgcn_cosf(fb), INV ? __builtin_amdgcn_sinf(fb) : -__builtin_amdgcn_sinf(fb));
; #pragma unroll
;     for (int m = 0; m < R; ++m) {
;       if (m & hl) continue;
;       const int k = m & (hl - 1); const int j = k * (8 / hl);
;       const float2 wc = make_float2(c16(j), INV ? s16(j) : -s16(j));
;       const float2 tw = cmul(wb, wc);
;       if (!INV) { const float2 p = x[m], q = x[m + hl]; x[m] = make_float2(p.x + q.x, p.y + q.y); x[m + hl] = cmul(make_float2(p.x - q.x, p.y - q.y), tw); }
;       else { const float2 p = x[m], q = cmul(x[m + hl], tw); x[m] = make_float2(p.x + q.x, p.y + q.y); x[m + hl] = make_float2(p.x - q.x, p.y - q.y); }
;     }
;   }
	v_mul_f32_e32 v88, v32, v76
	v_mul_f32_e32 v89, v32, v77
	v_sub_f32_e32 v68, v72, v74
	v_sub_f32_e32 v69, v73, v75
	v_add_f32_e32 v60, v60, v64
	v_add_f32_e32 v61, v61, v65
	v_add_f32_e32 v62, v62, v66
	v_add_f32_e32 v63, v63, v67
	v_fma_f32 v96, v28, v76, -v89
	v_fma_f32 v97, v28, v77, v88
	v_mul_f32_e32 v70, v32, v68
	v_mul_f32_e32 v71, v32, v69
	v_sub_f32_e32 v64, v60, v62
	v_sub_f32_e32 v65, v61, v63
	v_ashrrev_i32_e32 v3, 4, v2

; __device__ __forceinline__ float2 cmul(float2 a, float2 b) { return make_float2(a.x * b.x - a.y * b.y, a.x * b.y + a.y * b.x); }
; template <int LR, bool INV>
; __device__ __forceinline__ void fft_stages(float2 (&x)[1 << LR], const int r, const int s) {
;   constexpr int R = 1 << LR;
; #pragma unroll
;   for (int st = 0; st < LR; ++st) {
;     const int hl = INV ? (1 << st) : (R >> (st + 1));
;     const float fb = (float)r * (0.5f / (float)(hl * s));
;     const float2 wb = make_float2(__builtin_amdgcn_cosf(fb), INV ? __builtin_amdgcn_sinf(fb) : -__builtin_amdgcn_sinf(fb));
; #pragma unroll
;     for (int m = 0; m < R; ++m) {
;       if (m & hl) continue;
;       const int k = m & (hl - 1); const int j = k * (8 / hl);
;       const float2 wc = make_float2(c16(j), INV ? s16(j) : -s16(j));
;       const float2 tw = cmul(wb, wc);
;       if (!INV) { const float2 p = x[m], q = x[m + hl]; x[m] = make_float2(p.x + q.x, p.y + q.y); x[m + hl] = cmul(make_float2(p.x - q.x, p.y - q.y), tw); }
;       else { const float2 p = x[m], q = cmul(x[m + hl], tw); x[m] = make_float2(p.x + q.x, p.y + q.y); x[m + hl] = make_float2(p.x - q.x, p.y - q.y); }
;     }
;   }
	v_fma_f32 v76, v28, v68, -v71
	v_fma_f32 v77, v28, v69, v70
	v_mul_f32_e32 v66, v32, v64
	v_mul_f32_e32 v67, v32, v65
	v_lshl_add_u32 v3, v3, 3, v29

; __device__ __forceinline__ float2 cmul(float2 a, float2 b) { return make_float2(a.x * b.x - a.y * b.y, a.x * b.y + a.y * b.x); }
; template <int LR, bool INV>
; __device__ __forceinline__ void fft_stages(float2 (&x)[1 << LR], const int r, const int s) {
;   constexpr int R = 1 << LR;
; #pragma unroll
;   for (int st = 0; st < LR; ++st) {
;     const int hl = INV ? (1 << st) : (R >> (st + 1));
;     const float fb = (float)r * (0.5f / (float)(hl * s));
;     const float2 wb = make_float2(__builtin_amdgcn_cosf(fb), INV ? __builtin_amdgcn_sinf(fb) : -__builtin_amdgcn_sinf(fb));
; #pragma unroll
;     for (int m = 0; m < R; ++m) {
;       if (m & hl) continue;
;       const int k = m & (hl - 1); const int j = k * (8 / hl);
;       const float2 wc = make_float2(c16(j), INV ? s16(j) : -s16(j));
;       const float2 tw = cmul(wb, wc);
;       if (!INV) { const float2 p = x[m], q = x[m + hl]; x[m] = make_float2(p.x + q.x, p.y + q.y); x[m + hl] = cmul(make_float2(p.x - q.x, p.y - q.y), tw); }
;       else { const float2 p = x[m], q = cmul(x[m + hl], tw); x[m] = make_float2(p.x + q.x, p.y + q.y); x[m + hl] = make_float2(p.x - q.x, p.y - q.y); }
;     }
;   }
	v_fma_f32 v68, v28, v64, -v67
	v_fma_f32 v69, v28, v65, v66
	v_add_f32_e32 v60, v60, v62
	v_add_f32_e32 v61, v61, v63

; __device__ __forceinline__ float2 cmul(float2 a, float2 b) { return make_float2(a.x * b.x - a.y * b.y, a.x * b.y + a.y * b.x); }
; #define tid ltid()
; template <int LR, bool INV>
; __device__ __forceinline__ void fft_stages(float2 (&x)[1 << LR], const int r, const int s) {
;   constexpr int R = 1 << LR;
; #pragma unroll
;   for (int st = 0; st < LR; ++st) {
;     const int hl = INV ? (1 << st) : (R >> (st + 1));
;     const float fb = (float)r * (0.5f / (float)(hl * s));
;     const float2 wb = make_float2(__builtin_amdgcn_cosf(fb), INV ? __builtin_amdgcn_sinf(fb) : -__builtin_amdgcn_sinf(fb));
; #pragma unroll
;     for (int m = 0; m < R; ++m) {
;       if (m & hl) continue;
;       const int k = m & (hl - 1); const int j = k * (8 / hl);
;       const float2 wc = make_float2(c16(j), INV ? s16(j) : -s16(j));
;       const float2 tw = cmul(wb, wc);
;       if (!INV) { const float2 p = x[m], q = x[m + hl]; x[m] = make_float2(p.x + q.x, p.y + q.y); x[m + hl] = cmul(make_float2(p.x - q.x, p.y - q.y), tw); }
;       else { const float2 p = x[m], q = cmul(x[m + hl], tw); x[m] = make_float2(p.x + q.x, p.y + q.y); x[m + hl] = make_float2(p.x - q.x, p.y - q.y); }
;     }
;   }
; template <int LR>
; __device__ __forceinline__ void fft_first(float2* X, const bf16* __restrict__ u0, const bf16* __restrict__ u1, const int tid) {
;     ...
;   fft_stages<LR, false>(x, tid, 512);
; #pragma unroll
;   for (int m = 0; m < R; ++m) X[PIDX(tid + 512 * m)] = x[m];
;   __syncthreads();
	ds_write_b64 v3, v[60:61]
	ds_write_b64 v33, v[68:69] offset:4096
	v_add_f32_e32 v60, v72, v74
	v_add_f32_e32 v61, v73, v75
	ds_write_b64 v37, v[60:61] offset:8192
	ds_write_b64 v39, v[76:77] offset:12288
	v_add_f32_e32 v60, v80, v86
	v_add_f32_e32 v61, v81, v87
	v_add_f32_e32 v62, v84, v90
	v_add_f32_e32 v63, v85, v91
	v_add_u32_e32 v3, 0x1000, v2
	v_sub_f32_e32 v64, v60, v62
	v_sub_f32_e32 v65, v61, v63
	v_ashrrev_i32_e32 v3, 4, v3
	v_mul_f32_e32 v66, v32, v64
	v_mul_f32_e32 v67, v32, v65
	v_lshl_add_u32 v33, v3, 3, v29
	v_add_u32_e32 v3, 0x1200, v2
	v_ashrrev_i32_e32 v3, 4, v3
	v_lshl_add_u32 v37, v3, 3, v29
	v_add_u32_e32 v3, 0x1400, v2
	v_ashrrev_i32_e32 v3, 4, v3
	v_lshl_add_u32 v39, v3, 3, v29
	v_add_u32_e32 v3, 0x1600, v2
	v_fma_f32 v68, v28, v64, -v67
	v_fma_f32 v65, v28, v65, v66
	v_add_f32_e32 v60, v60, v62
	v_add_f32_e32 v61, v61, v63
	v_ashrrev_i32_e32 v3, 4, v3
	v_mov_b32_e32 v69, v65
	ds_write_b64 v41, v[60:61] offset:16384
	ds_write_b64 v43, v[68:69] offset:20480
	v_lshl_add_u32 v41, v3, 3, v29
	v_add_u32_e32 v3, 0x1800, v2
	v_ashrrev_i32_e32 v3, 4, v3
	v_lshl_add_u32 v43, v3, 3, v29
	v_add_u32_e32 v3, 0x1a00, v2
	v_add_f32_e32 v60, v92, v94
	v_add_f32_e32 v61, v93, v95
	v_ashrrev_i32_e32 v3, 4, v3
	ds_write_b64 v45, v[60:61] offset:24576
	ds_write_b64 v47, v[96:97] offset:28672
	v_lshl_add_u32 v47, v3, 3, v29
	v_add_u32_e32 v3, 0x1c00, v2
	v_add_u32_e32 v2, 0x1e00, v2
	v_ashrrev_i32_e32 v3, 4, v3
	v_ashrrev_i32_e32 v2, 4, v2
	v_lshl_add_u32 v49, v3, 3, v29
	v_lshl_add_u32 v29, v2, 3, v29
	v_mov_b32_e32 v2, v35
	v_mul_f32_e32 v3, v22, v2
	v_mul_f32_e32 v2, v23, v2
	v_fma_f32 v60, v22, v34, -v2
	v_fma_f32 v61, v23, v34, v3
	v_mov_b32_e32 v2, v31

; __device__ __forceinline__ float2 cmul(float2 a, float2 b) { return make_float2(a.x * b.x - a.y * b.y, a.x * b.y + a.y * b.x); }
; template <int LR, bool INV>
; __device__ __forceinline__ void fft_stages(float2 (&x)[1 << LR], const int r, const int s) {
;   constexpr int R = 1 << LR;
; #pragma unroll
;   for (int st = 0; st < LR; ++st) {
;     const int hl = INV ? (1 << st) : (R >> (st + 1));
;     const float fb = (float)r * (0.5f / (float)(hl * s));
;     const float2 wb = make_float2(__builtin_amdgcn_cosf(fb), INV ? __builtin_amdgcn_sinf(fb) : -__builtin_amdgcn_sinf(fb));
; #pragma unroll
;     for (int m = 0; m < R; ++m) {
;       if (m & hl) continue;
;       const int k = m & (hl - 1); const int j = k * (8 / hl);
;       const float2 wc = make_float2(c16(j), INV ? s16(j) : -s16(j));
;       const float2 tw = cmul(wb, wc);
;       if (!INV) { const float2 p = x[m], q = x[m + hl]; x[m] = make_float2(p.x + q.x, p.y + q.y); x[m + hl] = cmul(make_float2(p.x - q.x, p.y - q.y), tw); }
;       else { const float2 p = x[m], q = cmul(x[m + hl], tw); x[m] = make_float2(p.x + q.x, p.y + q.y); x[m + hl] = make_float2(p.x - q.x, p.y - q.y); }
;     }
;   }
	v_mul_f32_e32 v3, v24, v2
	v_mul_f32_e32 v2, v25, v2
	v_fma_f32 v22, v24, v30, -v2
	v_fma_f32 v23, v25, v30, v3
	v_mov_b32_e32 v2, v27

; __device__ __forceinline__ float2 cmul(float2 a, float2 b) { return make_float2(a.x * b.x - a.y * b.y, a.x * b.y + a.y * b.x); }
; template <int LR, bool INV>
; __device__ __forceinline__ void fft_stages(float2 (&x)[1 << LR], const int r, const int s) {
;   constexpr int R = 1 << LR;
; #pragma unroll
;   for (int st = 0; st < LR; ++st) {
;     const int hl = INV ? (1 << st) : (R >> (st + 1));
;     const float fb = (float)r * (0.5f / (float)(hl * s));
;     const float2 wb = make_float2(__builtin_amdgcn_cosf(fb), INV ? __builtin_amdgcn_sinf(fb) : -__builtin_amdgcn_sinf(fb));
; #pragma unroll
;     for (int m = 0; m < R; ++m) {
;       if (m & hl) continue;
;       const int k = m & (hl - 1); const int j = k * (8 / hl);
;       const float2 wc = make_float2(c16(j), INV ? s16(j) : -s16(j));
;       const float2 tw = cmul(wb, wc);
;       if (!INV) { const float2 p = x[m], q = x[m + hl]; x[m] = make_float2(p.x + q.x, p.y + q.y); x[m + hl] = cmul(make_float2(p.x - q.x, p.y - q.y), tw); }
;       else { const float2 p = x[m], q = cmul(x[m + hl], tw); x[m] = make_float2(p.x + q.x, p.y + q.y); x[m + hl] = make_float2(p.x - q.x, p.y - q.y); }
;     }
;   }
	v_mul_f32_e32 v3, v14, v2
	v_mul_f32_e32 v2, v15, v2
	v_fma_f32 v24, v14, v26, -v2
	v_fma_f32 v25, v15, v26, v3
	v_mov_b32_e32 v2, v21

; __device__ __forceinline__ float2 cmul(float2 a, float2 b) { return make_float2(a.x * b.x - a.y * b.y, a.x * b.y + a.y * b.x); }
; template <int LR, bool INV>
; __device__ __forceinline__ void fft_stages(float2 (&x)[1 << LR], const int r, const int s) {
;   constexpr int R = 1 << LR;
; #pragma unroll
;   for (int st = 0; st < LR; ++st) {
;     const int hl = INV ? (1 << st) : (R >> (st + 1));
;     const float fb = (float)r * (0.5f / (float)(hl * s));
;     const float2 wb = make_float2(__builtin_amdgcn_cosf(fb), INV ? __builtin_amdgcn_sinf(fb) : -__builtin_amdgcn_sinf(fb));
; #pragma unroll
;     for (int m = 0; m < R; ++m) {
;       if (m & hl) continue;
;       const int k = m & (hl - 1); const int j = k * (8 / hl);
;       const float2 wc = make_float2(c16(j), INV ? s16(j) : -s16(j));
;       const float2 tw = cmul(wb, wc);
;       if (!INV) { const float2 p = x[m], q = x[m + hl]; x[m] = make_float2(p.x + q.x, p.y + q.y); x[m + hl] = cmul(make_float2(p.x - q.x, p.y - q.y), tw); }
;       else { const float2 p = x[m], q = cmul(x[m + hl], tw); x[m] = make_float2(p.x + q.x, p.y + q.y); x[m + hl] = make_float2(p.x - q.x, p.y - q.y); }
;     }
;   }
	v_mul_f32_e32 v3, v16, v2
	v_mul_f32_e32 v2, v17, v2
	v_fma_f32 v14, v16, v20, -v2
	v_fma_f32 v15, v17, v20, v3
	v_mov_b32_e32 v2, v19

; __device__ __forceinline__ float2 cmul(float2 a, float2 b) { return make_float2(a.x * b.x - a.y * b.y, a.x * b.y + a.y * b.x); }
; template <int LR, bool INV>
; __device__ __forceinline__ void fft_stages(float2 (&x)[1 << LR], const int r, const int s) {
;   constexpr int R = 1 << LR;
; #pragma unroll
;   for (int st = 0; st < LR; ++st) {
;     const int hl = INV ? (1 << st) : (R >> (st + 1));
;     const float fb = (float)r * (0.5f / (float)(hl * s));
;     const float2 wb = make_float2(__builtin_amdgcn_cosf(fb), INV ? __builtin_amdgcn_sinf(fb) : -__builtin_amdgcn_sinf(fb));
; #pragma unroll
;     for (int m = 0; m < R; ++m) {
;       if (m & hl) continue;
;       const int k = m & (hl - 1); const int j = k * (8 / hl);
;       const float2 wc = make_float2(c16(j), INV ? s16(j) : -s16(j));
;       const float2 tw = cmul(wb, wc);
;       if (!INV) { const float2 p = x[m], q = x[m + hl]; x[m] = make_float2(p.x + q.x, p.y + q.y); x[m + hl] = cmul(make_float2(p.x - q.x, p.y - q.y), tw); }
;       else { const float2 p = x[m], q = cmul(x[m + hl], tw); x[m] = make_float2(p.x + q.x, p.y + q.y); x[m + hl] = make_float2(p.x - q.x, p.y - q.y); }
;     }
;   }
	v_mul_f32_e32 v3, v6, v2
	v_mul_f32_e32 v2, v7, v2
	v_fma_f32 v16, v6, v18, -v2
	v_fma_f32 v17, v7, v18, v3
	v_mov_b32_e32 v2, v13

; __device__ __forceinline__ float2 cmul(float2 a, float2 b) { return make_float2(a.x * b.x - a.y * b.y, a.x * b.y + a.y * b.x); }
; template <int LR, bool INV>
; __device__ __forceinline__ void fft_stages(float2 (&x)[1 << LR], const int r, const int s) {
;   constexpr int R = 1 << LR;
; #pragma unroll
;   for (int st = 0; st < LR; ++st) {
;     const int hl = INV ? (1 << st) : (R >> (st + 1));
;     const float fb = (float)r * (0.5f / (float)(hl * s));
;     const float2 wb = make_float2(__builtin_amdgcn_cosf(fb), INV ? __builtin_amdgcn_sinf(fb) : -__builtin_amdgcn_sinf(fb));
; #pragma unroll
;     for (int m = 0; m < R; ++m) {
;       if (m & hl) continue;
;       const int k = m & (hl - 1); const int j = k * (8 / hl);
;       const float2 wc = make_float2(c16(j), INV ? s16(j) : -s16(j));
;       const float2 tw = cmul(wb, wc);
;       if (!INV) { const float2 p = x[m], q = x[m + hl]; x[m] = make_float2(p.x + q.x, p.y + q.y); x[m + hl] = cmul(make_float2(p.x - q.x, p.y - q.y), tw); }
;       else { const float2 p = x[m], q = cmul(x[m + hl], tw); x[m] = make_float2(p.x + q.x, p.y + q.y); x[m + hl] = make_float2(p.x - q.x, p.y - q.y); }
;     }
;   }
	v_mul_f32_e32 v3, v54, v2
	v_mul_f32_e32 v2, v55, v2
	v_fma_f32 v6, v54, v12, -v2
	v_fma_f32 v7, v55, v12, v3
	v_mov_b32_e32 v2, v11

; __device__ __forceinline__ float2 cmul(float2 a, float2 b) { return make_float2(a.x * b.x - a.y * b.y, a.x * b.y + a.y * b.x); }
; template <int LR, bool INV>
; __device__ __forceinline__ void fft_stages(float2 (&x)[1 << LR], const int r, const int s) {
;   constexpr int R = 1 << LR;
; #pragma unroll
;   for (int st = 0; st < LR; ++st) {
;     const int hl = INV ? (1 << st) : (R >> (st + 1));
;     const float fb = (float)r * (0.5f / (float)(hl * s));
;     const float2 wb = make_float2(__builtin_amdgcn_cosf(fb), INV ? __builtin_amdgcn_sinf(fb) : -__builtin_amdgcn_sinf(fb));
; #pragma unroll
;     for (int m = 0; m < R; ++m) {
;       if (m & hl) continue;
;       const int k = m & (hl - 1); const int j = k * (8 / hl);
;       const float2 wc = make_float2(c16(j), INV ? s16(j) : -s16(j));
;       const float2 tw = cmul(wb, wc);
;       if (!INV) { const float2 p = x[m], q = x[m + hl]; x[m] = make_float2(p.x + q.x, p.y + q.y); x[m + hl] = cmul(make_float2(p.x - q.x, p.y - q.y), tw); }
;       else { const float2 p = x[m], q = cmul(x[m + hl], tw); x[m] = make_float2(p.x + q.x, p.y + q.y); x[m + hl] = make_float2(p.x - q.x, p.y - q.y); }
;     }
;   }
	v_mul_f32_e32 v3, v4, v2
	v_mul_f32_e32 v2, v5, v2
	v_fma_f32 v12, v4, v10, -v2
	v_fma_f32 v13, v5, v10, v3
	v_mov_b32_e32 v2, v9

; __device__ __forceinline__ float2 cmul(float2 a, float2 b) { return make_float2(a.x * b.x - a.y * b.y, a.x * b.y + a.y * b.x); }
; template <int LR, bool INV>
; __device__ __forceinline__ void fft_stages(float2 (&x)[1 << LR], const int r, const int s) {
;   constexpr int R = 1 << LR;
; #pragma unroll
;   for (int st = 0; st < LR; ++st) {
;     const int hl = INV ? (1 << st) : (R >> (st + 1));
;     const float fb = (float)r * (0.5f / (float)(hl * s));
;     const float2 wb = make_float2(__builtin_amdgcn_cosf(fb), INV ? __builtin_amdgcn_sinf(fb) : -__builtin_amdgcn_sinf(fb));
; #pragma unroll
;     for (int m = 0; m < R; ++m) {
;       if (m & hl) continue;
;       const int k = m & (hl - 1); const int j = k * (8 / hl);
;       const float2 wc = make_float2(c16(j), INV ? s16(j) : -s16(j));
;       const float2 tw = cmul(wb, wc);
;       if (!INV) { const float2 p = x[m], q = x[m + hl]; x[m] = make_float2(p.x + q.x, p.y + q.y); x[m + hl] = cmul(make_float2(p.x - q.x, p.y - q.y), tw); }
;       else { const float2 p = x[m], q = cmul(x[m + hl], tw); x[m] = make_float2(p.x + q.x, p.y + q.y); x[m + hl] = make_float2(p.x - q.x, p.y - q.y); }
;     }
;   }
	v_mul_f32_e32 v3, v52, v2
	v_mul_f32_e32 v2, v53, v2
	v_fma_f32 v4, v52, v8, -v2
	v_fma_f32 v5, v53, v8, v3

; __device__ __forceinline__ float2 cmul(float2 a, float2 b) { return make_float2(a.x * b.x - a.y * b.y, a.x * b.y + a.y * b.x); }
; template <int LR, bool INV>
; __device__ __forceinline__ void fft_stages(float2 (&x)[1 << LR], const int r, const int s) {
;   constexpr int R = 1 << LR;
; #pragma unroll
;   for (int st = 0; st < LR; ++st) {
;     const int hl = INV ? (1 << st) : (R >> (st + 1));
;     const float fb = (float)r * (0.5f / (float)(hl * s));
;     const float2 wb = make_float2(__builtin_amdgcn_cosf(fb), INV ? __builtin_amdgcn_sinf(fb) : -__builtin_amdgcn_sinf(fb));
; #pragma unroll
;     for (int m = 0; m < R; ++m) {
;       if (m & hl) continue;
;       const int k = m & (hl - 1); const int j = k * (8 / hl);
;       const float2 wc = make_float2(c16(j), INV ? s16(j) : -s16(j));
;       const float2 tw = cmul(wb, wc);
;       if (!INV) { const float2 p = x[m], q = x[m + hl]; x[m] = make_float2(p.x + q.x, p.y + q.y); x[m + hl] = cmul(make_float2(p.x - q.x, p.y - q.y), tw); }
;       else { const float2 p = x[m], q = cmul(x[m + hl], tw); x[m] = make_float2(p.x + q.x, p.y + q.y); x[m + hl] = make_float2(p.x - q.x, p.y - q.y); }
;     }
;   }
	v_sub_f32_e32 v2, v60, v16
	v_sub_f32_e32 v3, v61, v17
	v_mul_f32_e32 v8, v50, v2
	v_mul_f32_e32 v9, v50, v3
	v_fma_f32 v10, v48, v2, -v9
	v_fma_f32 v11, v48, v3, v8

; __device__ __forceinline__ float2 cmul(float2 a, float2 b) { return make_float2(a.x * b.x - a.y * b.y, a.x * b.y + a.y * b.x); }
; template <int LR, bool INV>
; __device__ __forceinline__ void fft_stages(float2 (&x)[1 << LR], const int r, const int s) {
;   constexpr int R = 1 << LR;
; #pragma unroll
;   for (int st = 0; st < LR; ++st) {
;     const int hl = INV ? (1 << st) : (R >> (st + 1));
;     const float fb = (float)r * (0.5f / (float)(hl * s));
;     const float2 wb = make_float2(__builtin_amdgcn_cosf(fb), INV ? __builtin_amdgcn_sinf(fb) : -__builtin_amdgcn_sinf(fb));
; #pragma unroll
;     for (int m = 0; m < R; ++m) {
;       if (m & hl) continue;
;       const int k = m & (hl - 1); const int j = k * (8 / hl);
;       const float2 wc = make_float2(c16(j), INV ? s16(j) : -s16(j));
;       const float2 tw = cmul(wb, wc);
;       if (!INV) { const float2 p = x[m], q = x[m + hl]; x[m] = make_float2(p.x + q.x, p.y + q.y); x[m + hl] = cmul(make_float2(p.x - q.x, p.y - q.y), tw); }
;       else { const float2 p = x[m], q = cmul(x[m + hl], tw); x[m] = make_float2(p.x + q.x, p.y + q.y); x[m + hl] = make_float2(p.x - q.x, p.y - q.y); }
;     }
;   }
	v_sub_f32_e32 v2, v22, v6
	v_sub_f32_e32 v3, v23, v7
	v_add_f32_e32 v6, v22, v6
	v_add_f32_e32 v7, v23, v7
	v_mul_f32_e32 v8, v78, v2
	v_mul_f32_e32 v9, v79, v3
	v_fma_f32 v18, v56, v2, -v9
	v_fma_f32 v19, v56, v3, v8

; __device__ __forceinline__ float2 cmul(float2 a, float2 b) { return make_float2(a.x * b.x - a.y * b.y, a.x * b.y + a.y * b.x); }
; template <int LR, bool INV>
; __device__ __forceinline__ void fft_stages(float2 (&x)[1 << LR], const int r, const int s) {
;   constexpr int R = 1 << LR;
; #pragma unroll
;   for (int st = 0; st < LR; ++st) {
;     const int hl = INV ? (1 << st) : (R >> (st + 1));
;     const float fb = (float)r * (0.5f / (float)(hl * s));
;     const float2 wb = make_float2(__builtin_amdgcn_cosf(fb), INV ? __builtin_amdgcn_sinf(fb) : -__builtin_amdgcn_sinf(fb));
; #pragma unroll
;     for (int m = 0; m < R; ++m) {
;       if (m & hl) continue;
;       const int k = m & (hl - 1); const int j = k * (8 / hl);
;       const float2 wc = make_float2(c16(j), INV ? s16(j) : -s16(j));
;       const float2 tw = cmul(wb, wc);
;       if (!INV) { const float2 p = x[m], q = x[m + hl]; x[m] = make_float2(p.x + q.x, p.y + q.y); x[m + hl] = cmul(make_float2(p.x - q.x, p.y - q.y), tw); }
;       else { const float2 p = x[m], q = cmul(x[m + hl], tw); x[m] = make_float2(p.x + q.x, p.y + q.y); x[m + hl] = make_float2(p.x - q.x, p.y - q.y); }
;     }
;   }
	v_sub_f32_e32 v2, v24, v12
	v_sub_f32_e32 v3, v25, v13
	v_mul_f32_e32 v8, v46, v2
	v_mul_f32_e32 v9, v46, v3
	v_fma_f32 v20, v44, v2, -v9
	v_fma_f32 v21, v44, v3, v8

; __device__ __forceinline__ float2 cmul(float2 a, float2 b) { return make_float2(a.x * b.x - a.y * b.y, a.x * b.y + a.y * b.x); }
; template <int LR, bool INV>
; __device__ __forceinline__ void fft_stages(float2 (&x)[1 << LR], const int r, const int s) {
;   constexpr int R = 1 << LR;
; #pragma unroll
;   for (int st = 0; st < LR; ++st) {
;     const int hl = INV ? (1 << st) : (R >> (st + 1));
;     const float fb = (float)r * (0.5f / (float)(hl * s));
;     const float2 wb = make_float2(__builtin_amdgcn_cosf(fb), INV ? __builtin_amdgcn_sinf(fb) : -__builtin_amdgcn_sinf(fb));
; #pragma unroll
;     for (int m = 0; m < R; ++m) {
;       if (m & hl) continue;
;       const int k = m & (hl - 1); const int j = k * (8 / hl);
;       const float2 wc = make_float2(c16(j), INV ? s16(j) : -s16(j));
;       const float2 tw = cmul(wb, wc);
;       if (!INV) { const float2 p = x[m], q = x[m + hl]; x[m] = make_float2(p.x + q.x, p.y + q.y); x[m + hl] = cmul(make_float2(p.x - q.x, p.y - q.y), tw); }
;       else { const float2 p = x[m], q = cmul(x[m + hl], tw); x[m] = make_float2(p.x + q.x, p.y + q.y); x[m + hl] = make_float2(p.x - q.x, p.y - q.y); }
;     }
;   }
	v_sub_f32_e32 v2, v14, v4
	v_sub_f32_e32 v3, v15, v5
	v_add_f32_e32 v4, v14, v4
	v_add_f32_e32 v5, v15, v5
	v_mul_f32_e32 v8, v82, v2
	v_mul_f32_e32 v9, v82, v3
	v_fma_f32 v26, v58, v2, -v9
	v_fma_f32 v27, v59, v3, v8

; __device__ __forceinline__ float2 cmul(float2 a, float2 b) { return make_float2(a.x * b.x - a.y * b.y, a.x * b.y + a.y * b.x); }
; template <int LR, bool INV>
; __device__ __forceinline__ void fft_stages(float2 (&x)[1 << LR], const int r, const int s) {
;   constexpr int R = 1 << LR;
; #pragma unroll
;   for (int st = 0; st < LR; ++st) {
;     const int hl = INV ? (1 << st) : (R >> (st + 1));
;     const float fb = (float)r * (0.5f / (float)(hl * s));
;     const float2 wb = make_float2(__builtin_amdgcn_cosf(fb), INV ? __builtin_amdgcn_sinf(fb) : -__builtin_amdgcn_sinf(fb));
; #pragma unroll
;     for (int m = 0; m < R; ++m) {
;       if (m & hl) continue;
;       const int k = m & (hl - 1); const int j = k * (8 / hl);
;       const float2 wc = make_float2(c16(j), INV ? s16(j) : -s16(j));
;       const float2 tw = cmul(wb, wc);
;       if (!INV) { const float2 p = x[m], q = x[m + hl]; x[m] = make_float2(p.x + q.x, p.y + q.y); x[m + hl] = cmul(make_float2(p.x - q.x, p.y - q.y), tw); }
;       else { const float2 p = x[m], q = cmul(x[m + hl], tw); x[m] = make_float2(p.x + q.x, p.y + q.y); x[m + hl] = make_float2(p.x - q.x, p.y - q.y); }
;     }
;   }
	v_sub_f32_e32 v2, v10, v20
	v_sub_f32_e32 v3, v11, v21
	v_mul_f32_e32 v8, v42, v2
	v_mul_f32_e32 v9, v42, v3
	v_fma_f32 v30, v36, v2, -v9
	v_fma_f32 v31, v36, v3, v8

; __device__ __forceinline__ float2 cmul(float2 a, float2 b) { return make_float2(a.x * b.x - a.y * b.y, a.x * b.y + a.y * b.x); }
; template <int LR, bool INV>
; __device__ __forceinline__ void fft_stages(float2 (&x)[1 << LR], const int r, const int s) {
;   constexpr int R = 1 << LR;
; #pragma unroll
;   for (int st = 0; st < LR; ++st) {
;     const int hl = INV ? (1 << st) : (R >> (st + 1));
;     const float fb = (float)r * (0.5f / (float)(hl * s));
;     const float2 wb = make_float2(__builtin_amdgcn_cosf(fb), INV ? __builtin_amdgcn_sinf(fb) : -__builtin_amdgcn_sinf(fb));
; #pragma unroll
;     for (int m = 0; m < R; ++m) {
;       if (m & hl) continue;
;       const int k = m & (hl - 1); const int j = k * (8 / hl);
;       const float2 wc = make_float2(c16(j), INV ? s16(j) : -s16(j));
;       const float2 tw = cmul(wb, wc);
;       if (!INV) { const float2 p = x[m], q = x[m + hl]; x[m] = make_float2(p.x + q.x, p.y + q.y); x[m + hl] = cmul(make_float2(p.x - q.x, p.y - q.y), tw); }
;       else { const float2 p = x[m], q = cmul(x[m + hl], tw); x[m] = make_float2(p.x + q.x, p.y + q.y); x[m + hl] = make_float2(p.x - q.x, p.y - q.y); }
;     }
;   }
	v_sub_f32_e32 v2, v18, v26
	v_sub_f32_e32 v3, v19, v27
	v_mul_f32_e32 v8, v40, v2
	v_mul_f32_e32 v9, v40, v3
	v_fma_f32 v34, v38, v2, -v9
	v_fma_f32 v35, v38, v3, v8

; __device__ __forceinline__ float2 cmul(float2 a, float2 b) { return make_float2(a.x * b.x - a.y * b.y, a.x * b.y + a.y * b.x); }
; template <int LR, bool INV>
; __device__ __forceinline__ void fft_stages(float2 (&x)[1 << LR], const int r, const int s) {
;   constexpr int R = 1 << LR;
; #pragma unroll
;   for (int st = 0; st < LR; ++st) {
;     const int hl = INV ? (1 << st) : (R >> (st + 1));
;     const float fb = (float)r * (0.5f / (float)(hl * s));
;     const float2 wb = make_float2(__builtin_amdgcn_cosf(fb), INV ? __builtin_amdgcn_sinf(fb) : -__builtin_amdgcn_sinf(fb));
; #pragma unroll
;     for (int m = 0; m < R; ++m) {
;       if (m & hl) continue;
;       const int k = m & (hl - 1); const int j = k * (8 / hl);
;       const float2 wc = make_float2(c16(j), INV ? s16(j) : -s16(j));
;       const float2 tw = cmul(wb, wc);
;       if (!INV) { const float2 p = x[m], q = x[m + hl]; x[m] = make_float2(p.x + q.x, p.y + q.y); x[m + hl] = cmul(make_float2(p.x - q.x, p.y - q.y), tw); }
;       else { const float2 p = x[m], q = cmul(x[m + hl], tw); x[m] = make_float2(p.x + q.x, p.y + q.y); x[m + hl] = make_float2(p.x - q.x, p.y - q.y); }
;     }
;   }
	v_sub_f32_e32 v2, v30, v34
	v_sub_f32_e32 v3, v31, v35
	v_mul_f32_e32 v8, v32, v2
	v_mul_f32_e32 v9, v32, v3
	v_fma_f32 v44, v28, v2, -v9
	v_fma_f32 v45, v28, v3, v8

; __device__ __forceinline__ float2 cmul(float2 a, float2 b) { return make_float2(a.x * b.x - a.y * b.y, a.x * b.y + a.y * b.x); }
; template <int LR, bool INV>
; __device__ __forceinline__ void fft_stages(float2 (&x)[1 << LR], const int r, const int s) {
;   constexpr int R = 1 << LR;
; #pragma unroll
;   for (int st = 0; st < LR; ++st) {
;     const int hl = INV ? (1 << st) : (R >> (st + 1));
;     const float fb = (float)r * (0.5f / (float)(hl * s));
;     const float2 wb = make_float2(__builtin_amdgcn_cosf(fb), INV ? __builtin_amdgcn_sinf(fb) : -__builtin_amdgcn_sinf(fb));
; #pragma unroll
;     for (int m = 0; m < R; ++m) {
;       if (m & hl) continue;
;       const int k = m & (hl - 1); const int j = k * (8 / hl);
;       const float2 wc = make_float2(c16(j), INV ? s16(j) : -s16(j));
;       const float2 tw = cmul(wb, wc);
;       if (!INV) { const float2 p = x[m], q = x[m + hl]; x[m] = make_float2(p.x + q.x, p.y + q.y); x[m + hl] = cmul(make_float2(p.x - q.x, p.y - q.y), tw); }
;       else { const float2 p = x[m], q = cmul(x[m + hl], tw); x[m] = make_float2(p.x + q.x, p.y + q.y); x[m + hl] = make_float2(p.x - q.x, p.y - q.y); }
;     }
;   }
	v_add_f32_e32 v2, v60, v16
	v_add_f32_e32 v3, v61, v17
	v_add_f32_e32 v8, v24, v12
	v_add_f32_e32 v9, v25, v13
	v_sub_f32_e32 v12, v2, v8
	v_sub_f32_e32 v13, v3, v9
	v_add_f32_e32 v2, v2, v8
	v_add_f32_e32 v3, v3, v9
	v_mul_f32_e32 v14, v42, v12
	v_mul_f32_e32 v15, v42, v13
	v_fma_f32 v16, v36, v12, -v15
	v_fma_f32 v17, v36, v13, v14

; __device__ __forceinline__ float2 cmul(float2 a, float2 b) { return make_float2(a.x * b.x - a.y * b.y, a.x * b.y + a.y * b.x); }
; template <int LR, bool INV>
; __device__ __forceinline__ void fft_stages(float2 (&x)[1 << LR], const int r, const int s) {
;   constexpr int R = 1 << LR;
; #pragma unroll
;   for (int st = 0; st < LR; ++st) {
;     const int hl = INV ? (1 << st) : (R >> (st + 1));
;     const float fb = (float)r * (0.5f / (float)(hl * s));
;     const float2 wb = make_float2(__builtin_amdgcn_cosf(fb), INV ? __builtin_amdgcn_sinf(fb) : -__builtin_amdgcn_sinf(fb));
; #pragma unroll
;     for (int m = 0; m < R; ++m) {
;       if (m & hl) continue;
;       const int k = m & (hl - 1); const int j = k * (8 / hl);
;       const float2 wc = make_float2(c16(j), INV ? s16(j) : -s16(j));
;       const float2 tw = cmul(wb, wc);
;       if (!INV) { const float2 p = x[m], q = x[m + hl]; x[m] = make_float2(p.x + q.x, p.y + q.y); x[m + hl] = cmul(make_float2(p.x - q.x, p.y - q.y), tw); }
;       else { const float2 p = x[m], q = cmul(x[m + hl], tw); x[m] = make_float2(p.x + q.x, p.y + q.y); x[m + hl] = make_float2(p.x - q.x, p.y - q.y); }
;     }
;   }
	v_sub_f32_e32 v12, v6, v4
	v_sub_f32_e32 v13, v7, v5
	v_add_f32_e32 v4, v6, v4
	v_add_f32_e32 v5, v7, v5
	v_mul_f32_e32 v14, v40, v12
	v_mul_f32_e32 v15, v40, v13
	v_fma_f32 v22, v38, v12, -v15
	v_fma_f32 v23, v38, v13, v14

; __device__ __forceinline__ float2 cmul(float2 a, float2 b) { return make_float2(a.x * b.x - a.y * b.y, a.x * b.y + a.y * b.x); }
; template <int LR, bool INV>
; __device__ __forceinline__ void fft_stages(float2 (&x)[1 << LR], const int r, const int s) {
;   constexpr int R = 1 << LR;
; #pragma unroll
;   for (int st = 0; st < LR; ++st) {
;     const int hl = INV ? (1 << st) : (R >> (st + 1));
;     const float fb = (float)r * (0.5f / (float)(hl * s));
;     const float2 wb = make_float2(__builtin_amdgcn_cosf(fb), INV ? __builtin_amdgcn_sinf(fb) : -__builtin_amdgcn_sinf(fb));
; #pragma unroll
;     for (int m = 0; m < R; ++m) {
;       if (m & hl) continue;
;       const int k = m & (hl - 1); const int j = k * (8 / hl);
;       const float2 wc = make_float2(c16(j), INV ? s16(j) : -s16(j));
;       const float2 tw = cmul(wb, wc);
;       if (!INV) { const float2 p = x[m], q = x[m + hl]; x[m] = make_float2(p.x + q.x, p.y + q.y); x[m + hl] = cmul(make_float2(p.x - q.x, p.y - q.y), tw); }
;       else { const float2 p = x[m], q = cmul(x[m + hl], tw); x[m] = make_float2(p.x + q.x, p.y + q.y); x[m + hl] = make_float2(p.x - q.x, p.y - q.y); }
;     }
;   }
	v_sub_f32_e32 v12, v16, v22
	v_sub_f32_e32 v13, v17, v23
	v_sub_f32_e32 v6, v2, v4
	v_sub_f32_e32 v7, v3, v5
	v_mul_f32_e32 v14, v32, v12
	v_mul_f32_e32 v15, v32, v13
	v_fma_f32 v24, v28, v12, -v15
	v_fma_f32 v25, v28, v13, v14
	v_mul_f32_e32 v8, v32, v6
	v_mul_f32_e32 v9, v32, v7

; __device__ __forceinline__ float2 cmul(float2 a, float2 b) { return make_float2(a.x * b.x - a.y * b.y, a.x * b.y + a.y * b.x); }
; template <int LR, bool INV>
; __device__ __forceinline__ void fft_stages(float2 (&x)[1 << LR], const int r, const int s) {
;   constexpr int R = 1 << LR;
; #pragma unroll
;   for (int st = 0; st < LR; ++st) {
;     const int hl = INV ? (1 << st) : (R >> (st + 1));
;     const float fb = (float)r * (0.5f / (float)(hl * s));
;     const float2 wb = make_float2(__builtin_amdgcn_cosf(fb), INV ? __builtin_amdgcn_sinf(fb) : -__builtin_amdgcn_sinf(fb));
; #pragma unroll
;     for (int m = 0; m < R; ++m) {
;       if (m & hl) continue;
;       const int k = m & (hl - 1); const int j = k * (8 / hl);
;       const float2 wc = make_float2(c16(j), INV ? s16(j) : -s16(j));
;       const float2 tw = cmul(wb, wc);
;       if (!INV) { const float2 p = x[m], q = x[m + hl]; x[m] = make_float2(p.x + q.x, p.y + q.y); x[m + hl] = cmul(make_float2(p.x - q.x, p.y - q.y), tw); }
;       else { const float2 p = x[m], q = cmul(x[m + hl], tw); x[m] = make_float2(p.x + q.x, p.y + q.y); x[m + hl] = make_float2(p.x - q.x, p.y - q.y); }
;     }
;   }
	v_fma_f32 v12, v28, v6, -v9
	v_fma_f32 v13, v28, v7, v8
	v_add_f32_e32 v2, v2, v4
	v_add_f32_e32 v3, v3, v5

; __device__ __forceinline__ float2 cmul(float2 a, float2 b) { return make_float2(a.x * b.x - a.y * b.y, a.x * b.y + a.y * b.x); }
; #define tid ltid()
; template <int LR, bool INV>
; __device__ __forceinline__ void fft_stages(float2 (&x)[1 << LR], const int r, const int s) {
;   constexpr int R = 1 << LR;
; #pragma unroll
;   for (int st = 0; st < LR; ++st) {
;     const int hl = INV ? (1 << st) : (R >> (st + 1));
;     const float fb = (float)r * (0.5f / (float)(hl * s));
;     const float2 wb = make_float2(__builtin_amdgcn_cosf(fb), INV ? __builtin_amdgcn_sinf(fb) : -__builtin_amdgcn_sinf(fb));
; #pragma unroll
;     for (int m = 0; m < R; ++m) {
;       if (m & hl) continue;
;       const int k = m & (hl - 1); const int j = k * (8 / hl);
;       const float2 wc = make_float2(c16(j), INV ? s16(j) : -s16(j));
;       const float2 tw = cmul(wb, wc);
;       if (!INV) { const float2 p = x[m], q = x[m + hl]; x[m] = make_float2(p.x + q.x, p.y + q.y); x[m + hl] = cmul(make_float2(p.x - q.x, p.y - q.y), tw); }
;       else { const float2 p = x[m], q = cmul(x[m + hl], tw); x[m] = make_float2(p.x + q.x, p.y + q.y); x[m + hl] = make_float2(p.x - q.x, p.y - q.y); }
;     }
;   }
; template <int LR>
; __device__ __forceinline__ void fft_first(float2* X, const bf16* __restrict__ u0, const bf16* __restrict__ u1, const int tid) {
;     ...
; #pragma unroll
;   for (int m = 0; m < R; ++m) X[PIDX(tid + 512 * m)] = x[m];
;   __syncthreads();
	ds_write_b64 v33, v[2:3] offset:32768
	ds_write_b64 v37, v[12:13] offset:36864
	v_add_f32_e32 v2, v16, v22
	v_add_f32_e32 v3, v17, v23
	ds_write_b64 v39, v[2:3] offset:40960
	ds_write_b64 v41, v[24:25] offset:45056
	v_add_f32_e32 v2, v10, v20
	v_add_f32_e32 v3, v11, v21
	v_add_f32_e32 v4, v18, v26
	v_add_f32_e32 v5, v19, v27
	v_sub_f32_e32 v6, v2, v4
	v_sub_f32_e32 v7, v3, v5
	v_add_f32_e32 v2, v2, v4
	v_add_f32_e32 v3, v3, v5
	v_mul_f32_e32 v8, v32, v6
	v_mul_f32_e32 v9, v32, v7
	v_fma_f32 v10, v28, v6, -v9
	v_fma_f32 v7, v28, v7, v8
	v_mov_b32_e32 v11, v7
	ds_write_b64 v43, v[2:3] offset:49152
	ds_write_b64 v47, v[10:11] offset:53248
	v_add_f32_e32 v2, v30, v34
	v_add_f32_e32 v3, v31, v35
	ds_write_b64 v49, v[2:3] offset:57344
	ds_write_b64 v29, v[44:45] offset:61440
	s_waitcnt lgkmcnt(0)
	s_barrier

; __device__ __forceinline__ unsigned short f2bf(float f) { unsigned u = __float_as_uint(f); return (unsigned short)((u + 0x7fffu + ((u >> 16) & 1u)) >> 16); }
; __device__ __forceinline__ unsigned f2bf(float f) { unsigned u = __float_as_uint(f); return (u + 0x7fffu + ((u >> 16) & 1u)) >> 16; }
; __device__ __forceinline__ float2 cmul(float2 a, float2 b) { return make_float2(a.x * b.x - a.y * b.y, a.x * b.y + a.y * b.x); }
; #define tid ltid()
; template <int LR, bool INV>
; __device__ __forceinline__ void fft_stages(float2 (&x)[1 << LR], const int r, const int s) {
;   constexpr int R = 1 << LR;
; #pragma unroll
;   for (int st = 0; st < LR; ++st) {
;     const int hl = INV ? (1 << st) : (R >> (st + 1));
;     const float fb = (float)r * (0.5f / (float)(hl * s));
;     const float2 wb = make_float2(__builtin_amdgcn_cosf(fb), INV ? __builtin_amdgcn_sinf(fb) : -__builtin_amdgcn_sinf(fb));
; #pragma unroll
;     for (int m = 0; m < R; ++m) {
;       if (m & hl) continue;
;       const int k = m & (hl - 1); const int j = k * (8 / hl);
;       const float2 wc = make_float2(c16(j), INV ? s16(j) : -s16(j));
;       const float2 tw = cmul(wb, wc);
;       if (!INV) { const float2 p = x[m], q = x[m + hl]; x[m] = make_float2(p.x + q.x, p.y + q.y); x[m + hl] = cmul(make_float2(p.x - q.x, p.y - q.y), tw); }
;       else { const float2 p = x[m], q = cmul(x[m + hl], tw); x[m] = make_float2(p.x + q.x, p.y + q.y); x[m + hl] = make_float2(p.x - q.x, p.y - q.y); }
;     }
;   }
; template <int LR>
; __device__ __forceinline__ void fft_last(float2* X, bf16* __restrict__ u0, bf16* __restrict__ u1, const int tid) {
;   constexpr int R = 1 << LR;
;   float2 x[R];
; #pragma unroll
;   for (int m = 0; m < R; ++m) x[m] = X[PIDX(tid + 512 * m)];
;   fft_stages<LR, true>(x, tid, 512);
; #pragma unroll
;   for (int m = 0; m < R / 2; ++m) { u0[tid + 512 * m] = (bf16)f2bf(x[m].x); u1[tid + 512 * m] = (bf16)f2bf(x[m].y); }
;   __syncthreads();
.LBB0_690:
	v_mov_b32_e32 v2, v208
	s_nop 0
	v_add_u32_e32 v4, 0x200, v2
	v_lshl_add_u32 v12, v2, 3, 0
	v_ashrrev_i32_e32 v4, 4, v4
	v_lshl_add_u32 v6, v4, 3, v12
	v_add_u32_e32 v4, 0x400, v2
	v_ashrrev_i32_e32 v4, 4, v4
	v_add_u32_e32 v13, 0xa00, v2
	v_lshl_add_u32 v8, v4, 3, v12
	v_add_u32_e32 v4, 0x600, v2
	v_ashrrev_i32_e32 v13, 4, v13
	v_ashrrev_i32_e32 v3, 4, v2
	v_ashrrev_i32_e32 v4, 4, v4
	v_lshl_add_u32 v14, v13, 3, v12
	v_add_u32_e32 v13, 0xc00, v2
	v_cvt_f32_i32_e32 v20, v2
	v_lshl_add_u32 v3, v3, 3, v12
	v_lshl_add_u32 v10, v4, 3, v12
	v_ashrrev_i32_e32 v13, 4, v13
	ds_read_b64 v[4:5], v3
	ds_read_b64 v[6:7], v6 offset:4096
	ds_read_b64 v[8:9], v8 offset:8192
	ds_read_b64 v[10:11], v10 offset:12288
	v_add_u32_e32 v3, 0x800, v2
	v_lshl_add_u32 v16, v13, 3, v12
	v_add_u32_e32 v13, 0xe00, v2
	v_ashrrev_i32_e32 v3, 4, v3
	v_ashrrev_i32_e32 v13, 4, v13
	v_lshl_add_u32 v3, v3, 3, v12
	v_lshl_add_u32 v18, v13, 3, v12
	v_mul_f32_e32 v12, 0x3a800000, v20
	v_cos_f32_e32 v21, v12
	v_sin_f32_e32 v22, v12
	ds_read_b64 v[12:13], v3 offset:16384
	ds_read_b64 v[14:15], v14 offset:20480
	ds_read_b64 v[16:17], v16 offset:24576
	ds_read_b64 v[18:19], v18 offset:28672
	v_fmamk_f32 v3, v22, 0x80000000, v21
	v_fmac_f32_e32 v22, 0, v21
	s_waitcnt lgkmcnt(6)
	v_mul_f32_e32 v21, v22, v7
	v_mul_f32_e32 v7, v3, v7
	v_fmac_f32_e32 v7, v22, v6
	v_add_f32_e32 v23, v5, v7
	v_sub_f32_e32 v5, v5, v7
	s_waitcnt lgkmcnt(4)
	v_mul_f32_e32 v7, v22, v11
	v_mul_f32_e32 v11, v3, v11
	v_fma_f32 v21, v3, v6, -v21
	v_fma_f32 v7, v3, v10, -v7
	v_fmac_f32_e32 v11, v22, v10
	v_add_f32_e32 v6, v4, v21
	v_sub_f32_e32 v4, v4, v21
	v_add_f32_e32 v10, v8, v7
	v_add_f32_e32 v21, v9, v11
	v_sub_f32_e32 v7, v8, v7
	v_sub_f32_e32 v8, v9, v11
	s_waitcnt lgkmcnt(2)
	v_mul_f32_e32 v9, v22, v15
	v_fma_f32 v9, v3, v14, -v9
	v_mul_f32_e32 v11, v3, v15
	v_fmac_f32_e32 v11, v22, v14
	v_add_f32_e32 v14, v12, v9
	v_sub_f32_e32 v9, v12, v9
	s_waitcnt lgkmcnt(0)
	v_mul_f32_e32 v12, v22, v19
	v_fma_f32 v12, v3, v18, -v12
	v_mul_f32_e32 v3, v3, v19
	v_fmac_f32_e32 v3, v22, v18
	v_mul_f32_e32 v18, 0x3a000000, v20
	v_cos_f32_e32 v19, v18
	v_sin_f32_e32 v18, v18
	v_add_f32_e32 v15, v13, v11
	v_sub_f32_e32 v11, v13, v11
	v_add_f32_e32 v13, v16, v12
	v_add_f32_e32 v22, v17, v3
	v_sub_f32_e32 v12, v16, v12
	v_sub_f32_e32 v3, v17, v3
	v_fmamk_f32 v16, v18, 0x80000000, v19
	v_fma_f32 v17, 0, v19, v18
	v_mul_f32_e32 v24, v17, v21
	v_mul_f32_e32 v21, v16, v21
	v_fmac_f32_e32 v21, v17, v10
	v_add_f32_e32 v25, v23, v21
	v_sub_f32_e32 v21, v23, v21
	v_fma_f32 v23, v19, 0, -v18
	v_fmac_f32_e32 v19, 0, v18
	v_mul_f32_e32 v18, v19, v8
	v_mul_f32_e32 v8, v23, v8
	v_fma_f32 v24, v16, v10, -v24
	v_fmac_f32_e32 v8, v19, v7
	v_add_f32_e32 v10, v6, v24
	v_sub_f32_e32 v6, v6, v24
	v_add_f32_e32 v24, v5, v8
	v_sub_f32_e32 v5, v5, v8
	v_mul_f32_e32 v8, v17, v22
	v_fma_f32 v8, v16, v13, -v8
	v_mul_f32_e32 v16, v16, v22
	v_fmac_f32_e32 v16, v17, v13
	v_fma_f32 v18, v23, v7, -v18
	v_add_f32_e32 v13, v14, v8
	v_add_f32_e32 v17, v15, v16
	v_sub_f32_e32 v8, v14, v8
	v_sub_f32_e32 v14, v15, v16
	v_mul_f32_e32 v16, 0x39800000, v20
	v_add_f32_e32 v7, v4, v18
	v_sub_f32_e32 v4, v4, v18
	v_cos_f32_e32 v18, v16
	v_sin_f32_e32 v16, v16
	v_mul_f32_e32 v15, v19, v3
	v_fma_f32 v15, v23, v12, -v15
	v_mul_f32_e32 v3, v23, v3
	v_fmac_f32_e32 v3, v19, v12
	v_add_f32_e32 v12, v9, v15
	v_sub_f32_e32 v9, v9, v15
	v_fma_f32 v15, 0, v18, v16
	v_add_f32_e32 v19, v11, v3
	v_sub_f32_e32 v3, v11, v3
	v_fmamk_f32 v11, v16, 0x80000000, v18
	v_mul_f32_e32 v20, v15, v17
	v_fma_f32 v20, v11, v13, -v20
	v_mul_f32_e32 v11, v11, v17
	v_fmac_f32_e32 v11, v15, v13
	v_mul_f32_e32 v13, 0x3f3504f3, v16
	v_fma_f32 v15, v18, s71, -v13
	v_fmamk_f32 v17, v18, 0x3f3504f3, v13
	v_add_f32_e32 v10, v10, v20
	v_mul_f32_e32 v20, v17, v19
	v_mul_f32_e32 v19, v15, v19
	v_fmac_f32_e32 v19, v17, v12
	v_fma_f32 v17, v18, 0, -v16
	v_fma_f32 v16, 0, v16, v18
	v_fma_f32 v20, v15, v12, -v20
	v_add_f32_e32 v12, v24, v19
	v_mul_f32_e32 v19, v16, v14
	v_mul_f32_e32 v14, v17, v14
	v_fmac_f32_e32 v14, v16, v8
	v_fma_f32 v13, v18, s70, -v13
	v_fma_f32 v19, v17, v8, -v19
	v_add_f32_e32 v8, v21, v14
	v_mul_f32_e32 v14, v15, v3
	v_mul_f32_e32 v3, v13, v3
	v_fmac_f32_e32 v3, v15, v9
	v_fma_f32 v14, v13, v9, -v14
	v_add_f32_e32 v13, v5, v3
	v_bfe_u32 v3, v10, 16, 1
	v_add3_u32 v10, v10, v3, s65
	v_ashrrev_i32_e32 v3, 31, v2
	v_lshlrev_b64 v[2:3], 1, v[2:3]
	v_add_f32_e32 v11, v25, v11
	v_add_f32_e32 v9, v4, v14
	v_lshl_add_u64 v[4:5], s[40:41], 0, v[2:3]
	s_waitcnt vmcnt(0)
	global_store_short_d16_hi v[4:5], v10, off
	v_bfe_u32 v10, v11, 16, 1
	v_add_f32_e32 v7, v7, v20
	v_add3_u32 v10, v11, v10, s65
	v_lshl_add_u64 v[2:3], s[42:43], 0, v[2:3]
	global_store_short_d16_hi v[2:3], v10, off
	v_bfe_u32 v10, v7, 16, 1
	v_add3_u32 v7, v7, v10, s65
	global_store_short_d16_hi v[4:5], v7, off offset:1024
	v_bfe_u32 v7, v12, 16, 1
	v_add_f32_e32 v6, v6, v19
	v_add3_u32 v7, v12, v7, s65
	global_store_short_d16_hi v[2:3], v7, off offset:1024
	v_bfe_u32 v7, v6, 16, 1
	v_add3_u32 v6, v6, v7, s65
	global_store_short_d16_hi v[4:5], v6, off offset:2048
	v_bfe_u32 v6, v8, 16, 1
	v_add3_u32 v6, v8, v6, s65
	global_store_short_d16_hi v[2:3], v6, off offset:2048
	v_bfe_u32 v6, v9, 16, 1
	v_add3_u32 v6, v9, v6, s65
	global_store_short_d16_hi v[4:5], v6, off offset:3072
	v_bfe_u32 v4, v13, 16, 1
	v_add3_u32 v4, v13, v4, s65
	global_store_short_d16_hi v[2:3], v4, off offset:3072
	s_waitcnt vmcnt(63) expcnt(7) lgkmcnt(15)
	s_barrier
	s_cbranch_execnz .LBB0_668
; __device__ __forceinline__ float2 cmul(float2 a, float2 b) { return make_float2(a.x * b.x - a.y * b.y, a.x * b.y + a.y * b.x); }
; #define tid ltid()
; template <int LR, bool INV>
; __device__ __forceinline__ void fft_stages(float2 (&x)[1 << LR], const int r, const int s) {
;   constexpr int R = 1 << LR;
; #pragma unroll
;   for (int st = 0; st < LR; ++st) {
;     const int hl = INV ? (1 << st) : (R >> (st + 1));
;     const float fb = (float)r * (0.5f / (float)(hl * s));
;     const float2 wb = make_float2(__builtin_amdgcn_cosf(fb), INV ? __builtin_amdgcn_sinf(fb) : -__builtin_amdgcn_sinf(fb));
; #pragma unroll
;     for (int m = 0; m < R; ++m) {
;       if (m & hl) continue;
;       const int k = m & (hl - 1); const int j = k * (8 / hl);
;       const float2 wc = make_float2(c16(j), INV ? s16(j) : -s16(j));
;       const float2 tw = cmul(wb, wc);
;       if (!INV) { const float2 p = x[m], q = x[m + hl]; x[m] = make_float2(p.x + q.x, p.y + q.y); x[m + hl] = cmul(make_float2(p.x - q.x, p.y - q.y), tw); }
;       else { const float2 p = x[m], q = cmul(x[m + hl], tw); x[m] = make_float2(p.x + q.x, p.y + q.y); x[m + hl] = make_float2(p.x - q.x, p.y - q.y); }
;     }
;   }
; template <int LR>
; __device__ __forceinline__ void fft_last(float2* X, bf16* __restrict__ u0, bf16* __restrict__ u1, const int tid) {
;   constexpr int R = 1 << LR;
;   float2 x[R];
; #pragma unroll
;   for (int m = 0; m < R; ++m) x[m] = X[PIDX(tid + 512 * m)];
;   fft_stages<LR, true>(x, tid, 512);
.LBB0_691:
	v_mov_b32_e32 v2, v208
	s_nop 0
	v_add_u32_e32 v4, 0x200, v2
	v_lshl_add_u32 v28, v2, 3, 0
	v_ashrrev_i32_e32 v4, 4, v4
	v_lshl_add_u32 v6, v4, 3, v28
	v_add_u32_e32 v4, 0x400, v2
	v_ashrrev_i32_e32 v4, 4, v4
	v_add_u32_e32 v12, 0xa00, v2
	v_lshl_add_u32 v8, v4, 3, v28
	v_add_u32_e32 v4, 0x600, v2
	v_ashrrev_i32_e32 v12, 4, v12
	v_ashrrev_i32_e32 v3, 4, v2
	v_ashrrev_i32_e32 v4, 4, v4
	v_lshl_add_u32 v14, v12, 3, v28
	v_add_u32_e32 v12, 0xc00, v2
	v_lshl_add_u32 v3, v3, 3, v28
	v_lshl_add_u32 v10, v4, 3, v28
	v_ashrrev_i32_e32 v12, 4, v12
	v_add_u32_e32 v20, 0x1200, v2
	ds_read_b64 v[4:5], v3
	ds_read_b64 v[6:7], v6 offset:4096
	ds_read_b64 v[8:9], v8 offset:8192
	ds_read_b64 v[10:11], v10 offset:12288
	v_add_u32_e32 v3, 0x800, v2
	v_lshl_add_u32 v16, v12, 3, v28
	v_add_u32_e32 v12, 0xe00, v2
	v_ashrrev_i32_e32 v20, 4, v20
	v_ashrrev_i32_e32 v3, 4, v3
	v_ashrrev_i32_e32 v12, 4, v12
	v_lshl_add_u32 v22, v20, 3, v28
	v_add_u32_e32 v20, 0x1400, v2
	v_lshl_add_u32 v3, v3, 3, v28
	v_lshl_add_u32 v18, v12, 3, v28
	v_ashrrev_i32_e32 v20, 4, v20
	v_add_u32_e32 v29, 0x1a00, v2
	ds_read_b64 v[12:13], v3 offset:16384
	ds_read_b64 v[14:15], v14 offset:20480
	ds_read_b64 v[16:17], v16 offset:24576
	ds_read_b64 v[18:19], v18 offset:28672
	v_add_u32_e32 v3, 0x1000, v2
	v_lshl_add_u32 v24, v20, 3, v28
	v_add_u32_e32 v20, 0x1600, v2
	v_ashrrev_i32_e32 v29, 4, v29
	v_ashrrev_i32_e32 v3, 4, v3
	v_ashrrev_i32_e32 v20, 4, v20
	v_lshl_add_u32 v30, v29, 3, v28
	v_add_u32_e32 v29, 0x1c00, v2
	v_cvt_f32_i32_e32 v36, v2
	v_lshl_add_u32 v3, v3, 3, v28
	v_lshl_add_u32 v26, v20, 3, v28
	v_ashrrev_i32_e32 v29, 4, v29
	ds_read_b64 v[20:21], v3 offset:32768
	ds_read_b64 v[22:23], v22 offset:36864
	ds_read_b64 v[24:25], v24 offset:40960
	ds_read_b64 v[26:27], v26 offset:45056
	v_add_u32_e32 v3, 0x1800, v2
	v_lshl_add_u32 v32, v29, 3, v28
	v_add_u32_e32 v29, 0x1e00, v2
	v_ashrrev_i32_e32 v3, 4, v3
	v_ashrrev_i32_e32 v29, 4, v29
	v_lshl_add_u32 v3, v3, 3, v28
	v_lshl_add_u32 v34, v29, 3, v28
	v_mul_f32_e32 v28, 0x3a800000, v36
	v_cos_f32_e32 v37, v28
	v_sin_f32_e32 v38, v28
	ds_read_b64 v[28:29], v3 offset:49152
	ds_read_b64 v[30:31], v30 offset:53248
	ds_read_b64 v[32:33], v32 offset:57344
	ds_read_b64 v[34:35], v34 offset:61440
	v_fmamk_f32 v3, v38, 0x80000000, v37
	v_fmac_f32_e32 v38, 0, v37
	s_waitcnt lgkmcnt(14)
	v_mul_f32_e32 v37, v38, v7
	v_mul_f32_e32 v7, v3, v7
	v_fmac_f32_e32 v7, v38, v6
	v_add_f32_e32 v39, v5, v7
	v_sub_f32_e32 v5, v5, v7
	s_waitcnt lgkmcnt(12)
	v_mul_f32_e32 v7, v38, v11
	v_mul_f32_e32 v11, v3, v11
	v_fma_f32 v37, v3, v6, -v37
	v_fma_f32 v7, v3, v10, -v7
	v_fmac_f32_e32 v11, v38, v10
	v_add_f32_e32 v6, v4, v37
	v_sub_f32_e32 v4, v4, v37
	v_add_f32_e32 v10, v8, v7
	v_add_f32_e32 v37, v9, v11
	v_sub_f32_e32 v7, v8, v7
	v_sub_f32_e32 v8, v9, v11
	s_waitcnt lgkmcnt(10)
	v_mul_f32_e32 v9, v38, v15
	v_fma_f32 v9, v3, v14, -v9
	v_mul_f32_e32 v11, v3, v15
	v_fmac_f32_e32 v11, v38, v14
	v_add_f32_e32 v14, v12, v9
	v_sub_f32_e32 v9, v12, v9
	s_waitcnt lgkmcnt(8)
	v_mul_f32_e32 v12, v38, v19
	v_add_f32_e32 v15, v13, v11
	v_sub_f32_e32 v11, v13, v11
	v_fma_f32 v12, v3, v18, -v12
	v_mul_f32_e32 v13, v3, v19
	v_fmac_f32_e32 v13, v38, v18
	v_add_f32_e32 v18, v16, v12
	v_sub_f32_e32 v12, v16, v12
	s_waitcnt lgkmcnt(6)
	v_mul_f32_e32 v16, v38, v23
	v_add_f32_e32 v19, v17, v13
	v_sub_f32_e32 v13, v17, v13
	v_fma_f32 v16, v3, v22, -v16
	v_mul_f32_e32 v17, v3, v23
	v_fmac_f32_e32 v17, v38, v22
	v_add_f32_e32 v22, v20, v16
	v_sub_f32_e32 v16, v20, v16
	s_waitcnt lgkmcnt(4)
	v_mul_f32_e32 v20, v38, v27
	v_add_f32_e32 v23, v21, v17
	v_sub_f32_e32 v17, v21, v17
	v_fma_f32 v20, v3, v26, -v20
	v_mul_f32_e32 v21, v3, v27
	v_fmac_f32_e32 v21, v38, v26
	v_add_f32_e32 v26, v24, v20
	v_sub_f32_e32 v20, v24, v20
	s_waitcnt lgkmcnt(2)
	v_mul_f32_e32 v24, v38, v31
	v_add_f32_e32 v27, v25, v21
	v_sub_f32_e32 v21, v25, v21
	v_fma_f32 v24, v3, v30, -v24
	v_mul_f32_e32 v25, v3, v31
	v_fmac_f32_e32 v25, v38, v30
	v_add_f32_e32 v30, v28, v24
	v_sub_f32_e32 v24, v28, v24
	s_waitcnt lgkmcnt(0)
	v_mul_f32_e32 v28, v38, v35
	v_fma_f32 v28, v3, v34, -v28
	v_mul_f32_e32 v3, v3, v35
	v_fmac_f32_e32 v3, v38, v34
	v_mul_f32_e32 v34, 0x3a000000, v36
	v_cos_f32_e32 v35, v34
	v_sin_f32_e32 v34, v34
	v_add_f32_e32 v31, v29, v25
	v_sub_f32_e32 v25, v29, v25
	v_add_f32_e32 v29, v32, v28
	v_add_f32_e32 v38, v33, v3
	v_sub_f32_e32 v28, v32, v28
	v_sub_f32_e32 v3, v33, v3
	v_fmamk_f32 v32, v34, 0x80000000, v35
	v_fma_f32 v33, 0, v35, v34
	v_mul_f32_e32 v40, v33, v37
	v_mul_f32_e32 v37, v32, v37
	v_fmac_f32_e32 v37, v33, v10
	v_add_f32_e32 v41, v39, v37
	v_sub_f32_e32 v37, v39, v37
	v_fma_f32 v39, v35, 0, -v34
	v_fmac_f32_e32 v35, 0, v34
	v_mul_f32_e32 v34, v35, v8
	v_mul_f32_e32 v8, v39, v8
	v_fma_f32 v40, v32, v10, -v40
	v_fmac_f32_e32 v8, v35, v7
	v_add_f32_e32 v10, v6, v40
	v_sub_f32_e32 v6, v6, v40
	v_add_f32_e32 v40, v5, v8
	v_sub_f32_e32 v5, v5, v8
	v_mul_f32_e32 v8, v33, v19
	v_mul_f32_e32 v19, v32, v19
	v_fma_f32 v34, v39, v7, -v34
	v_fma_f32 v8, v32, v18, -v8
	v_fmac_f32_e32 v19, v33, v18
	v_add_f32_e32 v7, v4, v34
	v_sub_f32_e32 v4, v4, v34
	v_add_f32_e32 v18, v14, v8
	v_add_f32_e32 v34, v15, v19
	v_sub_f32_e32 v8, v14, v8
	v_sub_f32_e32 v14, v15, v19
	v_mul_f32_e32 v15, v35, v13
	v_mul_f32_e32 v13, v39, v13
	v_fmac_f32_e32 v13, v35, v12
	v_fma_f32 v15, v39, v12, -v15
	v_add_f32_e32 v19, v11, v13
	v_sub_f32_e32 v11, v11, v13
	v_mul_f32_e32 v13, v33, v27
	v_add_f32_e32 v12, v9, v15
	v_sub_f32_e32 v9, v9, v15
	v_fma_f32 v13, v32, v26, -v13
	v_mul_f32_e32 v15, v32, v27
	v_fmac_f32_e32 v15, v33, v26
	v_add_f32_e32 v26, v22, v13
	v_sub_f32_e32 v13, v22, v13
	v_mul_f32_e32 v22, v35, v21
; __device__ __forceinline__ unsigned short f2bf(float f) { unsigned u = __float_as_uint(f); return (unsigned short)((u + 0x7fffu + ((u >> 16) & 1u)) >> 16); }
; __device__ __forceinline__ unsigned f2bf(float f) { unsigned u = __float_as_uint(f); return (u + 0x7fffu + ((u >> 16) & 1u)) >> 16; }
; __device__ __forceinline__ float2 cmul(float2 a, float2 b) { return make_float2(a.x * b.x - a.y * b.y, a.x * b.y + a.y * b.x); }
; #define tid ltid()
; template <int LR, bool INV>
; __device__ __forceinline__ void fft_stages(float2 (&x)[1 << LR], const int r, const int s) {
;   constexpr int R = 1 << LR;
; #pragma unroll
;   for (int st = 0; st < LR; ++st) {
;     const int hl = INV ? (1 << st) : (R >> (st + 1));
;     const float fb = (float)r * (0.5f / (float)(hl * s));
;     const float2 wb = make_float2(__builtin_amdgcn_cosf(fb), INV ? __builtin_amdgcn_sinf(fb) : -__builtin_amdgcn_sinf(fb));
; #pragma unroll
;     for (int m = 0; m < R; ++m) {
;       if (m & hl) continue;
;       const int k = m & (hl - 1); const int j = k * (8 / hl);
;       const float2 wc = make_float2(c16(j), INV ? s16(j) : -s16(j));
;       const float2 tw = cmul(wb, wc);
;       if (!INV) { const float2 p = x[m], q = x[m + hl]; x[m] = make_float2(p.x + q.x, p.y + q.y); x[m + hl] = cmul(make_float2(p.x - q.x, p.y - q.y), tw); }
;       else { const float2 p = x[m], q = cmul(x[m + hl], tw); x[m] = make_float2(p.x + q.x, p.y + q.y); x[m + hl] = make_float2(p.x - q.x, p.y - q.y); }
;     }
;   }
; template <int LR>
; __device__ __forceinline__ void fft_last(float2* X, bf16* __restrict__ u0, bf16* __restrict__ u1, const int tid) {
;     ...
;   fft_stages<LR, true>(x, tid, 512);
; #pragma unroll
;   for (int m = 0; m < R / 2; ++m) { u0[tid + 512 * m] = (bf16)f2bf(x[m].x); u1[tid + 512 * m] = (bf16)f2bf(x[m].y); }
;   __syncthreads();
	v_fma_f32 v22, v39, v20, -v22
	v_mul_f32_e32 v21, v39, v21
	v_fmac_f32_e32 v21, v35, v20
	v_add_f32_e32 v20, v16, v22
	v_sub_f32_e32 v16, v16, v22
	v_mul_f32_e32 v22, v32, v38
	v_add_f32_e32 v27, v23, v15
	v_sub_f32_e32 v15, v23, v15
	v_add_f32_e32 v23, v17, v21
	v_sub_f32_e32 v17, v17, v21
	v_mul_f32_e32 v21, v33, v38
	v_fmac_f32_e32 v22, v33, v29
	v_fma_f32 v21, v32, v29, -v21
	v_add_f32_e32 v32, v31, v22
	v_sub_f32_e32 v22, v31, v22
	v_mul_f32_e32 v31, 0x39800000, v36
	v_cos_f32_e32 v33, v31
	v_sin_f32_e32 v31, v31
	v_add_f32_e32 v29, v30, v21
	v_sub_f32_e32 v21, v30, v21
	v_mul_f32_e32 v30, v35, v3
	v_fma_f32 v30, v39, v28, -v30
	v_mul_f32_e32 v3, v39, v3
	v_fmac_f32_e32 v3, v35, v28
	v_add_f32_e32 v28, v24, v30
	v_sub_f32_e32 v24, v24, v30
	v_fma_f32 v30, 0, v33, v31
	v_add_f32_e32 v35, v25, v3
	v_sub_f32_e32 v3, v25, v3
	v_fmamk_f32 v25, v31, 0x80000000, v33
	v_mul_f32_e32 v38, v30, v34
	v_fma_f32 v38, v25, v18, -v38
	v_mul_f32_e32 v34, v25, v34
	v_fmac_f32_e32 v34, v30, v18
	v_add_f32_e32 v18, v10, v38
	v_sub_f32_e32 v10, v10, v38
	v_mul_f32_e32 v38, 0x3f3504f3, v31
	v_add_f32_e32 v39, v41, v34
	v_sub_f32_e32 v34, v41, v34
	v_fma_f32 v41, v33, s71, -v38
	v_fmamk_f32 v42, v33, 0x3f3504f3, v38
	v_mul_f32_e32 v43, v42, v19
	v_mul_f32_e32 v19, v41, v19
	v_fmac_f32_e32 v19, v42, v12
	v_fma_f32 v43, v41, v12, -v43
	v_add_f32_e32 v44, v40, v19
	v_sub_f32_e32 v19, v40, v19
	v_fma_f32 v40, v33, 0, -v31
	v_fma_f32 v31, 0, v31, v33
	v_add_f32_e32 v12, v7, v43
	v_sub_f32_e32 v7, v7, v43
	v_mul_f32_e32 v43, v31, v14
	v_mul_f32_e32 v14, v40, v14
	v_fmac_f32_e32 v14, v31, v8
	v_fma_f32 v33, v33, s70, -v38
	v_add_f32_e32 v45, v37, v14
	v_sub_f32_e32 v14, v37, v14
	v_mul_f32_e32 v37, v41, v11
	v_mul_f32_e32 v11, v33, v11
	v_fmac_f32_e32 v11, v41, v9
	v_add_f32_e32 v38, v5, v11
	v_sub_f32_e32 v5, v5, v11
	v_mul_f32_e32 v11, v30, v32
	v_fma_f32 v11, v25, v29, -v11
	v_mul_f32_e32 v25, v25, v32
	v_fmac_f32_e32 v25, v30, v29
	v_add_f32_e32 v29, v26, v11
	v_sub_f32_e32 v11, v26, v11
	v_mul_f32_e32 v26, v42, v35
	v_add_f32_e32 v30, v27, v25
	v_sub_f32_e32 v25, v27, v25
	v_fma_f32 v26, v41, v28, -v26
	v_mul_f32_e32 v27, v41, v35
	v_fmac_f32_e32 v27, v42, v28
	v_add_f32_e32 v28, v20, v26
	v_sub_f32_e32 v20, v20, v26
	v_mul_f32_e32 v26, v31, v22
	v_fma_f32 v26, v40, v21, -v26
	v_mul_f32_e32 v22, v40, v22
	v_fmac_f32_e32 v22, v31, v21
	v_add_f32_e32 v21, v13, v26
	v_sub_f32_e32 v13, v13, v26
	v_mul_f32_e32 v26, 0x39000000, v36
	v_cos_f32_e32 v31, v26
	v_sin_f32_e32 v26, v26
	v_add_f32_e32 v32, v23, v27
	v_sub_f32_e32 v23, v23, v27
	v_add_f32_e32 v27, v15, v22
	v_sub_f32_e32 v15, v15, v22
	v_mul_f32_e32 v22, v41, v3
	v_fma_f32 v22, v33, v24, -v22
	v_mul_f32_e32 v3, v33, v3
	v_fmac_f32_e32 v3, v41, v24
	v_add_f32_e32 v24, v16, v22
	v_sub_f32_e32 v16, v16, v22
	v_fma_f32 v22, 0, v31, v26
	v_fma_f32 v37, v33, v9, -v37
	v_add_f32_e32 v33, v17, v3
	v_sub_f32_e32 v3, v17, v3
	v_fmamk_f32 v17, v26, 0x80000000, v31
	v_mul_f32_e32 v35, v22, v30
	v_fma_f32 v35, v17, v29, -v35
	v_mul_f32_e32 v17, v17, v30
	v_fmac_f32_e32 v17, v22, v29
	v_mul_f32_e32 v22, 0x3ec3ef15, v26
	v_mul_f32_e32 v30, 0x3f6c835e, v26
	v_add_f32_e32 v18, v18, v35
	v_fma_f32 v29, v31, s72, -v22
	v_fmamk_f32 v35, v31, 0x3ec3ef15, v30
	v_mul_f32_e32 v36, v35, v32
	v_mul_f32_e32 v32, v29, v32
	v_fmac_f32_e32 v32, v35, v28
	v_fma_f32 v36, v29, v28, -v36
	v_add_f32_e32 v28, v44, v32
	v_mul_f32_e32 v32, 0x3f3504f3, v26
	v_add_f32_e32 v12, v12, v36
	v_fma_f32 v35, v31, s71, -v32
	v_fmamk_f32 v36, v31, 0x3f3504f3, v32
	v_add_f32_e32 v9, v4, v37
	v_sub_f32_e32 v4, v4, v37
	v_mul_f32_e32 v37, v36, v27
	v_mul_f32_e32 v27, v35, v27
	v_fma_f32 v43, v40, v8, -v43
	v_fmac_f32_e32 v27, v36, v21
	v_add_f32_e32 v8, v6, v43
	v_fma_f32 v37, v35, v21, -v37
	v_add_f32_e32 v21, v45, v27
	v_fma_f32 v27, v31, s94, -v30
	v_fmamk_f32 v36, v31, 0x3f6c835e, v22
	v_add_f32_e32 v8, v8, v37
	v_mul_f32_e32 v37, v36, v33
	v_mul_f32_e32 v33, v27, v33
	v_fmac_f32_e32 v33, v36, v24
	v_fma_f32 v37, v27, v24, -v37
	v_add_f32_e32 v24, v38, v33
	v_fma_f32 v33, v31, 0, -v26
	v_fma_f32 v26, 0, v26, v31
	v_mul_f32_e32 v36, v26, v25
	v_mul_f32_e32 v25, v33, v25
	v_fmac_f32_e32 v25, v26, v11
	v_fma_f32 v36, v33, v11, -v36
	v_add_f32_e32 v11, v34, v25
	v_fma_f32 v25, v31, s92, -v30
	v_mul_f32_e32 v26, v29, v23
	v_mul_f32_e32 v23, v25, v23
	v_fma_f32 v26, v25, v20, -v26
	v_fmac_f32_e32 v23, v29, v20
	v_fma_f32 v20, v31, s70, -v32
	v_add_f32_e32 v19, v19, v23
	v_mul_f32_e32 v23, v35, v15
	v_mul_f32_e32 v15, v20, v15
	v_fmac_f32_e32 v15, v35, v13
	v_fma_f32 v23, v20, v13, -v23
	v_add_f32_e32 v13, v14, v15
	v_fma_f32 v14, v31, s73, -v22
	v_mul_f32_e32 v15, v27, v3
	v_mul_f32_e32 v3, v14, v3
	v_fma_f32 v15, v14, v16, -v15
	v_fmac_f32_e32 v3, v27, v16
	v_add_f32_e32 v14, v4, v15
	v_add_f32_e32 v15, v5, v3
	v_bfe_u32 v3, v18, 16, 1
	v_add3_u32 v16, v18, v3, s65
	v_ashrrev_i32_e32 v3, 31, v2
	v_lshlrev_b64 v[2:3], 1, v[2:3]
	v_add_f32_e32 v17, v39, v17
	v_lshl_add_u64 v[4:5], s[40:41], 0, v[2:3]
	s_waitcnt vmcnt(0)
	global_store_short_d16_hi v[4:5], v16, off
	v_bfe_u32 v16, v17, 16, 1
	v_add3_u32 v16, v17, v16, s65
	v_lshl_add_u64 v[2:3], s[42:43], 0, v[2:3]
	global_store_short_d16_hi v[2:3], v16, off
	v_bfe_u32 v16, v12, 16, 1
	v_add3_u32 v12, v12, v16, s65
	global_store_short_d16_hi v[4:5], v12, off offset:1024
	v_bfe_u32 v12, v28, 16, 1
	v_add3_u32 v12, v28, v12, s65
	global_store_short_d16_hi v[2:3], v12, off offset:1024
	v_bfe_u32 v12, v8, 16, 1
	v_add3_u32 v8, v8, v12, s65
	global_store_short_d16_hi v[4:5], v8, off offset:2048
	v_bfe_u32 v8, v21, 16, 1
	v_add_f32_e32 v9, v9, v37
	v_add3_u32 v8, v21, v8, s65
	global_store_short_d16_hi v[2:3], v8, off offset:2048
	v_bfe_u32 v8, v9, 16, 1
	v_add3_u32 v8, v9, v8, s65
	global_store_short_d16_hi v[4:5], v8, off offset:3072
	v_bfe_u32 v8, v24, 16, 1
	v_add_f32_e32 v10, v10, v36
	v_add3_u32 v8, v24, v8, s65
	global_store_short_d16_hi v[2:3], v8, off offset:3072
	v_bfe_u32 v8, v10, 16, 1
	v_add_co_u32_e32 v4, vcc, s64, v4
	v_add3_u32 v8, v10, v8, s65
	s_nop 0
	v_addc_co_u32_e32 v5, vcc, 0, v5, vcc
	global_store_short_d16_hi v[4:5], v8, off
	v_bfe_u32 v8, v11, 16, 1
	v_add_co_u32_e32 v2, vcc, s64, v2
	v_add_f32_e32 v7, v7, v26
	v_add3_u32 v8, v11, v8, s65
	v_addc_co_u32_e32 v3, vcc, 0, v3, vcc
	global_store_short_d16_hi v[2:3], v8, off
	v_bfe_u32 v8, v7, 16, 1
	v_add3_u32 v7, v7, v8, s65
	v_sub_f32_e32 v6, v6, v43
	global_store_short_d16_hi v[4:5], v7, off offset:1024
	v_bfe_u32 v7, v19, 16, 1
	v_add_f32_e32 v6, v6, v23
	v_add3_u32 v7, v19, v7, s65
	global_store_short_d16_hi v[2:3], v7, off offset:1024
	v_bfe_u32 v7, v6, 16, 1
	v_add3_u32 v6, v6, v7, s65
	global_store_short_d16_hi v[4:5], v6, off offset:2048
	v_bfe_u32 v6, v13, 16, 1
	v_add3_u32 v6, v13, v6, s65
	global_store_short_d16_hi v[2:3], v6, off offset:2048
	v_bfe_u32 v6, v14, 16, 1
	v_add3_u32 v6, v14, v6, s65
	global_store_short_d16_hi v[4:5], v6, off offset:3072
	v_bfe_u32 v4, v15, 16, 1
	v_add3_u32 v4, v15, v4, s65
	global_store_short_d16_hi v[2:3], v4, off offset:3072
	s_waitcnt vmcnt(63) expcnt(7) lgkmcnt(15)
	s_barrier
; #define tid ltid()
; __global__ void __launch_bounds__(NTHR, 2) mega_fwd(Args a_unused) {
;     ...
;           for (int pr = 0; pr < 4; ++pr) {
;             bf16* u0 = urow + (size_t)(2 * pr) * L; bf16* u1 = u0 + L;
;             if (gsel) fft_first<4>(A, u0, u1, tid); else fft_first<3>(A, u0, u1, tid);
;             fft_pass<3, false>(A, N, 6, tid); fft_pass<3, false>(A, N, 3, tid);
;             fft_mid(A, Hb, N, invN, tid);
;             fft_pass<3, true>(A, N, 3, tid); fft_pass<3, true>(A, N, 6, tid);
;             if (gsel) fft_last<4>(A, u0, u1, tid); else fft_last<3>(A, u0, u1, tid);
;           }
	s_branch .LBB0_668
